# one blockIdx%8 group keeps one batch through a layer: attention/pool/down units re-assigned inside the group, barriers inproj-attn, attn-outproj, gateup-down closed per XCC
# speedup vs baseline: 1.0209x; 1.0172x over previous
; __device__ __forceinline__ void attn_phase(LAS unsigned char* lds, const bf16* PROJ, bf16* CONCAT, const float* sinks) {
;     ...
;     bf16x8 qf[4][2];
;     ...
;     const bool xmap = (gridDim.x == 256);
;     ...
;     if ((int)blockIdx.x < NB * 64 * 2) { ATT_LOAD_KV(ATT_UNIT((int)blockIdx.x)); ATT_LOAD_Q(ATT_UNIT((int)blockIdx.x)); }
.LBB0_173:
	v_writelane_b32 v245, s82, 25
	s_nop 1
	v_writelane_b32 v245, s83, 26
	s_or_b64 exec, exec, s[0:1]
	s_and_b32 s100, s2, 7
	s_lshl_b32 s100, s100, 7
	s_bfe_u32 s101, s2, 0x10009
	s_lshl_b32 s101, s101, 6
	s_or_b32 s100, s100, s101
	s_bfe_u32 s101, s2, 0x50003
	s_lshl_b32 s101, s101, 1
	s_or_b32 s100, s100, s101
	s_bfe_u32 s101, s2, 0x10008
	s_or_b32 s100, s100, s101
	s_cmpk_eq_i32 s96, 0x100
	s_cselect_b32 s100, s100, s2
	s_lshl_b32 s1, s2, 5
	s_bfe_u32 s0, s2, 0x50003
	s_or_b32 s3, s0, s1
	s_and_b32 s4, s1, 0x80
	s_and_b32 s5, s2, 0xffffff00
	s_lshl_b32 s8, s3, 1
	s_cmpk_eq_i32 s96, 0x100
	v_writelane_b32 v245, s1, 27
	s_cselect_b64 s[0:1], -1, 0
	s_and_b64 s[0:1], s[0:1], exec
	s_mov_b32 s8, s100
	s_or_b32 s4, s4, s5
	s_cmpk_eq_i32 s96, 0x100
	s_cselect_b64 s[0:1], -1, 0
	s_and_b64 s[0:1], s[0:1], exec
	s_mov_b32 s4, s100
	s_lshr_b32 s5, s2, 1
	s_cmpk_eq_i32 s96, 0x100
	s_cselect_b64 s[80:81], -1, 0
	s_and_b64 s[0:1], s[80:81], exec
	s_lshr_b32 s0, s100, 1
	s_add_u32 s97, s94, 0x4000000
	s_addc_u32 s29, s95, 0
	s_add_u32 s82, s94, 0xc000000
	s_addc_u32 s83, s95, 0
	s_add_u32 s74, s94, 0x14000000
	s_addc_u32 s75, s95, 0
	s_add_u32 s24, s94, 0x1e000000
	s_addc_u32 s25, s95, 0
	s_cmpk_lt_i32 s2, 0x500
	s_cselect_b64 s[14:15], -1, 0
	s_ashr_i32 s27, s2, 31
	s_lshr_b32 s1, s27, 29
	v_writelane_b32 v245, s14, 28
	s_add_i32 s1, s2, s1
	s_ashr_i32 s3, s96, 31
	v_writelane_b32 v245, s15, 29
	s_ashr_i32 s14, s1, 3
	s_and_b32 s1, s1, -8
	s_sub_i32 s15, s2, s1
	s_waitcnt lgkmcnt(0)
;     __device__ bool next(int i, Unit& u) const { if (hot) { if (i >= rounds) return false; u.pm = (c % 8) * 2 + ((c / 8) & 1); u.pn = ((c / 8) >> 1) & 3; return true; } return so.next(i, u); }
;     __host__ __device__ bool next(int i, Unit& u) const {
;         const long L = (long)i * G + c; if (L >= nwg) return false;
;         int wgid = (int)L; { const int q = nwg / NXCD, r = nwg % NXCD, xcd = wgid % NXCD, off = wgid / NXCD; wgid = (xcd < r ? xcd * (q + 1) : r * (q + 1) + (xcd - r) * q) + off; }
;         const int nig = WGM * nN, gid = wgid / nig, fm = gid * WGM, gsz = (nM - fm) < WGM ? (nM - fm) : WGM;
;         u.pm = fm + ((wgid % nig) % gsz); u.pn = (wgid % nig) / gsz; if (rev) u.pm = nM - 1 - u.pm; return true;
; __device__ __forceinline__ void attn_phase(LAS unsigned char* lds, const bf16* PROJ, bf16* CONCAT, const float* sinks) {
;     ...
;     const bool xmap = (gridDim.x == 256);
;     ...
;     if ((int)blockIdx.x < NB * 64 * 2) { ATT_LOAD_KV(ATT_UNIT((int)blockIdx.x)); ATT_LOAD_Q(ATT_UNIT((int)blockIdx.x)); }
	v_cndmask_b32_e64 v0, 0, 1, s[80:81]
	s_cmpk_lt_i32 s2, 0x400
	s_cselect_b64 s[16:17], -1, 0
	v_readfirstlane_b32 s1, v0
	s_and_b32 s9, s0, 63
	s_ashr_i32 s0, s4, 7
	v_writelane_b32 v245, s16, 30
	s_mov_b32 s5, s100
	s_ashr_i32 s1, s0, 31
	v_writelane_b32 v245, s17, 31
	s_lshl_b64 s[16:17], s[0:1], 13
	s_lshl_b32 s0, s9, 7
	s_cmp_lg_u32 s9, 0
	s_cselect_b64 s[18:19], -1, 0
	v_writelane_b32 v245, s18, 32
	s_or_b32 s0, s16, s0
	s_add_u32 s0, s0, 0xffffff80
	v_writelane_b32 v245, s19, 33
	v_writelane_b32 v245, s16, 34
	s_addc_u32 s1, s17, -1
	s_mov_b32 s77, 0
	v_writelane_b32 v245, s17, 35
	v_writelane_b32 v245, s0, 36
	s_mov_b32 s78, s77
	s_mov_b32 s79, s77
	v_writelane_b32 v245, s1, 37
	s_lshl_b32 s0, s5, 7
	s_and_b32 s0, s0, 0x80
	s_add_u32 s0, s74, s0
	s_addc_u32 s1, s75, 0
	v_writelane_b32 v245, s0, 38
	s_lshl_b32 s84, s96, 3
	s_mov_b32 s76, s77
	v_writelane_b32 v245, s1, 39
	s_lshl_b32 s0, s5, 2
	s_and_b32 s0, s0, 4
	v_writelane_b32 v245, s0, 40
	s_lshl_b32 s0, s8, 6
	s_and_b32 s0, s0, 0x1f80
	v_writelane_b32 v245, s0, 41
	s_lshl_b32 s0, s15, 7
	s_add_u32 s1, s94, 0x802000
	v_writelane_b32 v245, s1, 42
	s_addc_u32 s1, s95, 0
	s_cmpk_lt_i32 s2, 0x1600
	v_writelane_b32 v245, s1, 43
	s_cselect_b64 s[4:5], -1, 0
	v_writelane_b32 v245, s4, 44
	s_cmp_lt_i32 s15, 0
	s_mul_i32 s1, s15, 0x81
	v_writelane_b32 v245, s5, 45
	s_movk_i32 s4, 0xa1
	s_cselect_b32 s4, s4, 0xa0
	s_mul_i32 s4, s15, s4
	s_cselect_b32 s1, s1, s0
	s_movk_i32 s0, 0x2c1
	s_cselect_b32 s16, s0, 0x2c0
	s_add_i32 s4, s4, s14
	s_mul_hi_i32 s0, s4, 0x66666667
	s_lshr_b32 s5, s0, 31
	s_ashr_i32 s0, s0, 3
	s_add_i32 s0, s0, s5
	s_mul_i32 s5, s0, 20
	s_sub_i32 s4, s4, s5
	s_lshl_b32 s8, s0, 2
	s_bfe_i32 s0, s4, 0x80000
	s_bfe_u32 s0, s0, 0x2000d
	s_add_i32 s5, s4, s0
	s_bfe_i32 s0, s5, 0x80000
	s_and_b32 s5, s5, 0xfc
	s_sub_i32 s4, s4, s5
	s_sext_i32_i16 s9, s0
	s_sext_i32_i8 s4, s4
	s_add_i32 s20, s8, s4
	s_ashr_i32 s4, s9, 2
	s_add_i32 s1, s1, s14
	v_writelane_b32 v245, s4, 46
	s_ashr_i32 s4, s1, 31
	s_lshr_b32 s4, s4, 28
	s_add_i32 s4, s1, s4
	s_ashr_i32 s5, s4, 4
	s_and_b32 s4, s4, 0xfff0
	s_sub_i32 s1, s1, s4
	s_bfe_i32 s4, s1, 0x80000
	s_bfe_u32 s4, s4, 0x2000d
	s_lshl_b32 s17, s5, 2
	s_add_i32 s5, s1, s4
	s_and_b32 s18, s5, 0xfc
	s_bfe_i32 s4, s5, 0x80000
	s_sub_i32 s5, s1, s18
	s_sext_i32_i16 s8, s4
	s_sext_i32_i8 s5, s5
	s_add_i32 s22, s17, s5
	s_ashr_i32 s5, s8, 2
	s_lshr_b32 s4, s8, 2
	v_writelane_b32 v245, s5, 47
	s_mov_b32 s8, s22
	s_lshr_b32 s0, s9, 2
	v_writelane_b32 v245, s8, 48
	s_bfe_i64 s[4:5], s[4:5], 0x100000
	s_ashr_i32 s23, s22, 31
	v_writelane_b32 v245, s9, 49
	s_lshl_b64 s[4:5], s[4:5], 19
	s_lshl_b64 s[8:9], s[22:23], 19
	v_writelane_b32 v245, s4, 50
	v_mov_b64_e32 v[206:207], s[78:79]
	s_movk_i32 s87, 0x1600
	v_writelane_b32 v245, s5, 51
	s_add_u32 s4, s24, s8
	s_addc_u32 s5, s25, s9
	s_add_u32 s8, s4, 0x40000
	v_writelane_b32 v245, s4, 52
	s_addc_u32 s9, s5, 0
	v_mov_b32_e32 v1, 0
	v_writelane_b32 v245, s5, 53
	s_mul_i32 s4, s15, s16
	s_add_i32 s4, s4, s14
	v_writelane_b32 v245, s8, 54
	s_mul_hi_i32 s5, s4, 0x2e8ba2e9
	v_mov_b32_e32 v193, 1
	v_writelane_b32 v245, s9, 55
	s_lshr_b32 s8, s5, 31
	s_ashr_i32 s5, s5, 4
	s_add_i32 s5, s5, s8
	s_lshl_b32 s8, s5, 2
	s_mulk_i32 s5, 0x58
	s_sub_i32 s5, s4, s5
	s_bfe_i32 s4, s5, 0x80000
	s_bfe_u32 s4, s4, 0x2000d
	s_add_i32 s9, s5, s4
	s_bfe_i32 s4, s9, 0x80000
	s_and_b32 s9, s9, 0xfc
	s_sub_i32 s5, s5, s9
	s_sext_i32_i16 s14, s4
	s_sext_i32_i8 s5, s5
	s_add_i32 s22, s8, s5
	s_ashr_i32 s5, s14, 2
	s_lshr_b32 s4, s14, 2
	v_writelane_b32 v245, s5, 56
	s_mov_b32 s8, s22
	v_writelane_b32 v245, s8, 57
	s_bfe_i64 s[4:5], s[4:5], 0x100000
	s_ashr_i32 s23, s22, 31
	v_writelane_b32 v245, s9, 58
	s_lshl_b64 s[4:5], s[4:5], 19
	s_lshl_b64 s[8:9], s[22:23], 19
	v_writelane_b32 v245, s4, 59
	v_mov_b64_e32 v[204:205], s[76:77]
	v_mov_b32_e32 v194, 0x358637bd
	v_writelane_b32 v245, s5, 60
	s_add_u32 s4, s97, s8
	s_addc_u32 s5, s29, s9
	s_add_u32 s8, s4, 0x40000
	v_writelane_b32 v245, s4, 61
	s_addc_u32 s9, s5, 0
	s_sub_i32 s1, s18, s1
	s_sext_i32_i8 s1, s1
	v_writelane_b32 v245, s5, 62
	s_sub_i32 s1, s1, s17
	v_writelane_b32 v245, s8, 63
	s_and_b32 s100, s2, 7
	s_lshl_b32 s100, s100, 6
	s_add_i32 s100, s100, 31
	s_cmpk_eq_i32 s96, 0x100
	s_cselect_b32 s100, s100, 0xff
	s_add_i32 s4, s1, s100
	s_mul_hi_i32 s1, s4, 0x160000
	v_writelane_b32 v244, s9, 0
	v_writelane_b32 v244, s4, 1
	s_mul_i32 s4, s4, 0x160000
	s_add_u32 s4, s74, s4
	s_addc_u32 s5, s75, s1
	s_add_u32 s8, s4, 0xb0000
	v_writelane_b32 v244, s4, 2
	s_addc_u32 s9, s5, 0
	s_bfe_i64 s[0:1], s[0:1], 0x100000
	v_writelane_b32 v244, s5, 3
	v_writelane_b32 v244, s8, 4
	s_mov_b32 s4, s20
	s_ashr_i32 s21, s20, 31
	v_writelane_b32 v244, s9, 5
	v_writelane_b32 v244, s4, 6
	s_lshl_b64 s[0:1], s[0:1], 19
	v_mov_b64_e32 v[162:163], 0x500
	v_writelane_b32 v244, s5, 7
	s_lshl_b64 s[4:5], s[20:21], 19
	v_writelane_b32 v244, s0, 8
	v_mov_b64_e32 v[164:165], 0x4ff
	v_mov_b32_e32 v195, 0xa00
	v_writelane_b32 v244, s1, 9
	s_add_u32 s0, s97, s4
	s_addc_u32 s1, s29, s5
	s_add_u32 s4, s0, 0x40000
	v_writelane_b32 v244, s0, 10
	s_addc_u32 s5, s1, 0
	s_lshl_b32 s86, s96, 4
	v_writelane_b32 v244, s1, 11
	v_writelane_b32 v244, s4, 12
	s_lshl_b32 s0, s96, 5
	v_mbcnt_hi_u32_b32 v196, -1, v56
	v_writelane_b32 v244, s5, 13
	v_writelane_b32 v244, s0, 14
	s_add_u32 s0, s94, 0x805000
	v_writelane_b32 v244, s0, 15
	s_addc_u32 s0, s95, 0
	v_writelane_b32 v244, s0, 16
	s_add_u32 s0, s94, 0x801000
	s_addc_u32 s1, s95, 0
	v_writelane_b32 v244, s0, 17
	v_mov_b32_e32 v197, 0xf149f2ca
	v_mov_b64_e32 v[166:167], 0x400
	v_writelane_b32 v244, s1, 18
	s_add_i32 s0, 0, 0x20040
	v_mov_b64_e32 v[168:169], 0x3ff
	v_mov_b64_e32 v[170:171], 0x1600
	v_mov_b64_e32 v[172:173], 0x15ff
	v_mov_b32_e32 v198, 0x6000
	s_movk_i32 s85, 0xa00
	v_writelane_b32 v244, s0, 19
	s_add_i32 s0, 0, 0x20044
	s_mov_b32 s78, 0xf149f2ca
	s_movk_i32 s79, 0x1000
	s_movk_i32 s30, 0x1ff0
	s_movk_i32 s31, 0xfff
	s_movk_i32 s14, 0x1ff
	s_mov_b32 s15, 0x32001000
	s_mov_b32 s68, 0xc001000
	s_mov_b32 s69, 0x2a001000
	s_brev_b32 s4, 32
	s_mov_b32 s5, 0x4001000
	s_movk_i32 s33, 0xdf
	s_mov_b64 s[18:19], -1
	s_mov_b64 s[8:9], 0x80
	s_mov_b32 s28, 0x3e000000
	s_mov_b32 s26, 0x3fb8aa3b
	s_mov_b64 s[34:35], 0x10000
	s_mov_b64 s[66:67], 0x800
	s_mov_b32 s16, s77
	s_barrier
	v_writelane_b32 v244, s0, 20
	s_branch .LBB0_177

; __device__ __forceinline__ unsigned xb_ld(unsigned* p)              { return __hip_atomic_load(p, __ATOMIC_RELAXED, __HIP_MEMORY_SCOPE_AGENT); }
; __device__ __forceinline__ unsigned xb_add(unsigned* p, unsigned v) { return __hip_atomic_fetch_add(p, v, __ATOMIC_RELAXED, __HIP_MEMORY_SCOPE_AGENT); }
; #define XB_SPIN(cond, bar) do { unsigned _sp = 0; while (cond) { __builtin_amdgcn_s_sleep(1); \
;     if ((++_sp & 255u) == 0u) { if (xb_ld(&(bar)[XB_TMO])) break; if (_sp > XB_SPIN_CAP) { atomicAdd(&(bar)[XB_TMO], 1u); break; } } } } while (0)
; __device__ __forceinline__ void xcd_barrier(const XcdBarrier& b) {
;     asm volatile("s_waitcnt vmcnt(0)" ::: "memory");
;     __syncthreads();
;     if (threadIdx.x == 0) {
;         unsigned* bar = b.bar;
;         __builtin_amdgcn_s_waitcnt(0);
;         unsigned nloc = b.st[0], nx = b.st[1];
;         if (nloc == 0u) { xcd_barrier_complete(bar, b.x, nloc, nx); b.st[0] = nloc; b.st[1] = nx; }
;         const unsigned old = xb_add(&bar[XB_XSUB(b.x)], 1u);
;         const unsigned gen = old / nloc;
;         if (old + 1u == (gen + 1u) * nloc) {
;             __builtin_amdgcn_fence(__ATOMIC_RELEASE, "agent");
;             asm volatile("s_waitcnt vmcnt(0)" ::: "memory");
;             const unsigned og = xb_add(&bar[XB_TOP], 1u);
;             const unsigned tg = og / nx;
;             if (og + 1u == (tg + 1u) * nx) xb_add(&bar[XB_TOPGEN], 1u);
;             else XB_SPIN(xb_ld(&bar[XB_TOPGEN]) == tg, bar);
;             __builtin_amdgcn_fence(__ATOMIC_ACQUIRE, "agent");
;             xb_add(&bar[XB_XGEN(b.x)], 1u);
;             asm volatile("s_waitcnt vmcnt(0)" ::: "memory");
;         } else {
;             XB_SPIN(xb_ld(&bar[XB_XGEN(b.x)]) == gen, bar);
.LBB0_241:
	s_andn2_saveexec_b64 s[16:17], s[20:21]
	s_cbranch_execz .LBB0_261
	v_readfirstlane_b32 s100, v247
	s_nop 3
	s_cmp_eq_u32 s100, 0
	s_cbranch_scc1 .Lxb_global_3
	v_readlane_b32 s100, v245, 18
	v_readlane_b32 s101, v245, 19
	v_mov_b32_e32 v251, 0
	v_mov_b32_e32 v250, 1
	s_nop 4
	global_atomic_add v251, v250, s[100:101]
	s_waitcnt vmcnt(1)
	s_branch .LBB0_261
.Lxb_global_3:
	s_mov_b64 s[16:17], exec
	buffer_wbl2 sc1
	s_waitcnt lgkmcnt(0)
	s_waitcnt vmcnt(0)
	v_mbcnt_lo_u32_b32 v0, s16, 0
	v_mbcnt_hi_u32_b32 v0, s17, v0
	v_cmp_eq_u32_e32 vcc, 0, v0
	s_and_saveexec_b64 s[20:21], vcc
	s_cbranch_execz .LBB0_244
	s_bcnt1_i32_b64 s16, s[16:17]
	v_mov_b32_e32 v3, s16
	v_readlane_b32 s16, v245, 20
	v_readlane_b32 s17, v245, 21
	s_nop 4
	global_atomic_add v3, v1, v3, s[16:17] sc0

; #define LAS __attribute__((address_space(3)))
; #define LAS __attribute__((address_space(3)))
; __device__ __forceinline__ void attn_phase(LAS unsigned char* lds, const bf16* PROJ, bf16* CONCAT, const float* sinks) {
;     ...
;     if ((int)blockIdx.x < NB * 64 * 2) { ATT_LOAD_KV(ATT_UNIT((int)blockIdx.x)); ATT_LOAD_Q(ATT_UNIT((int)blockIdx.x)); }
;     for (int ul = blockIdx.x; ul < NB * 64 * 2; ul += gridDim.x) {
;         const int u = ATT_UNIT(ul);
;         const int kh = u & 1, n = (u >> 1) & 63, b = u >> 7;
;         const int g = wave >> 1, h = kh * 4 + g;
;         const size_t qrow0 = (size_t)b * SEQ + n * 128 + (wave & 1) * 64 + fr;
; #pragma unroll
;         for (int i = 0; i < 4; ++i) { const int kj = lane + 64 * i;
;             *(LAS v4u*)(Ks + kj * 72 + wave * 8) = kv[i];
;             *(LAS v4u*)(Vs + kj * 72 + wave * 8) = vv[i]; }
;         __syncthreads();
;         if (ul + (int)gridDim.x < NB * 64 * 2) ATT_LOAD_KV(ATT_UNIT(ul + (int)gridDim.x));
.LBB0_269:
	s_andn2_b64 vcc, exec, s[80:81]
	s_mov_b32 s52, s23
	s_cbranch_vccnz .LBB0_271
	s_and_b32 s52, s23, 7
	s_lshl_b32 s52, s52, 7
	s_bfe_u32 s36, s23, 0x10009
	s_lshl_b32 s36, s36, 6
	s_or_b32 s52, s52, s36
	s_bfe_u32 s36, s23, 0x50003
	s_lshl_b32 s36, s36, 1
	s_or_b32 s52, s52, s36
	s_bfe_u32 s36, s23, 0x10008
	s_or_b32 s52, s52, s36
.LBB0_271:
	s_add_i32 s17, s23, s96
	s_cmpk_lt_i32 s17, 0x400
	s_cselect_b64 s[64:65], -1, 0
	s_cmpk_gt_i32 s17, 0x3ff
	s_cselect_b64 s[62:63], -1, 0
	s_and_b64 vcc, exec, s[62:63]
	s_waitcnt vmcnt(13)
	ds_write_b128 v149, v[4:7]
	s_waitcnt vmcnt(12)
	ds_write_b128 v149, v[8:11] offset:36864
	ds_write_b128 v149, v[12:15] offset:9216
	ds_write_b128 v149, v[16:19] offset:46080
	s_waitcnt vmcnt(11)
	ds_write_b128 v149, v[20:23] offset:18432
	s_waitcnt vmcnt(10)
	ds_write_b128 v149, v[24:27] offset:55296
	s_waitcnt vmcnt(9)
	ds_write_b128 v149, v[64:67] offset:27648
	s_waitcnt vmcnt(8)
	ds_write_b128 v149, v[60:63] offset:64512
	s_waitcnt lgkmcnt(0)
	s_barrier
	s_cbranch_vccnz .LBB0_278
	s_and_b32 s50, s17, 7
	s_lshl_b32 s50, s50, 7
	s_bfe_u32 s51, s17, 0x10009
	s_lshl_b32 s51, s51, 6
	s_or_b32 s50, s50, s51
	s_bfe_u32 s51, s17, 0x50003
	s_lshl_b32 s51, s51, 1
	s_or_b32 s50, s50, s51
	s_bfe_u32 s51, s17, 0x10008
	s_or_b32 s50, s50, s51
	s_and_b64 s[36:37], s[80:81], exec
	s_cselect_b32 s50, s50, s17
	s_mov_b32 s53, s50
	s_lshr_b32 s51, s50, 1
	s_and_b32 s54, s51, 63
	s_ashr_i32 s36, s50, 7
	s_ashr_i32 s37, s36, 31
	s_lshl_b64 s[36:37], s[36:37], 13
	s_lshl_b32 s55, s54, 7
	s_cmp_lg_u32 s54, 0
	s_cselect_b64 s[50:51], -1, 0
	s_or_b32 s36, s36, s55
	s_add_u32 s36, s36, 0xffffff80
	s_addc_u32 s37, s37, -1
	s_lshl_b32 s53, s53, 7
	s_and_b32 s76, s53, 0x80
	s_cmp_eq_u32 s54, 0
	v_lshl_add_u64 v[60:61], v[136:137], 0, s[76:77]
	s_mul_i32 s53, s37, 0xa00
	s_cbranch_scc1 .LBB0_275
	v_or_b32_e32 v4, s36, v128
	v_mad_u64_u32 v[8:9], s[54:55], v4, s85, v[60:61]
	v_add_u32_e32 v9, s53, v9
	global_load_dwordx4 v[4:7], v[8:9], off offset:1024
	s_nop 0
	global_load_dwordx4 v[8:11], v[8:9], off offset:1280
	s_andn2_b64 vcc, exec, s[50:51]
	s_cbranch_vccnz .LBB0_276

; #define LAS __attribute__((address_space(3)))
; #define LAS __attribute__((address_space(3)))
; #define ATT_LDK(t) do { kfr[t][0] = *(const LAS bf16x8*)(kp0 + (t) * 16 * 72); kfr[t][1] = *(const LAS bf16x8*)(kp0 + (t) * 16 * 72 + 32); } while (0)
; __device__ __forceinline__ void attn_phase(LAS unsigned char* lds, const bf16* PROJ, bf16* CONCAT, const float* sinks) {
;     ...
;         const float sink = sinks[h];
;         const int firstblk = (n == 0);
; #pragma unroll
;         for (int p = 0; p < 2; ++p) {
;             const int q16a = (wave & 1) * 4 + 2 * p, kt0 = q16a;
;             f32x4 st[2][10];
;             bf16x8 kfr[10][2];
;             const LAS bf16* kp0 = Ks + (16 * kt0 + fr) * 72 + 8 * fq;
;     ...
;             ATT_LDK(0);
; #pragma unroll
;             for (int t = 0; t < 10; ++t) {
;                 if (t + 1 < 10) ATT_LDK(t + 1);
; #pragma unroll
;                 for (int x = 0; x < 2; ++x) {
;                     if (x + 8 - t == 9 || x + 8 - t == -1) { st[x][t] = (f32x4){-1e30f, -1e30f, -1e30f, -1e30f}; continue; }
;                     f32x4 acc = (f32x4){0.f, 0.f, 0.f, 0.f};
;                     acc = __builtin_amdgcn_mfma_f32_16x16x32_bf16(kfr[t][0], qf[2 * p + x][0], acc, 0, 0, 0);
;                     acc = __builtin_amdgcn_mfma_f32_16x16x32_bf16(kfr[t][1], qf[2 * p + x][1], acc, 0, 0, 0);
;                     st[x][t] = acc;
;                 }
;             }
;     ...
;             float inv[2];
; #pragma unroll
;             for (int x = 0; x < 2; ++x) {
;                 float mx = -1e30f;
; #pragma unroll
;                 for (int t = 0; t < 10; ++t) {
;                     const int D = x + 8 - t;
;                     if (D == 9 || D == -1) continue;
;                     const bool tile_off = firstblk && (kt0 + t < 8);
; #pragma unroll
;                     for (int r = 0; r < 4; ++r) { const int dl = fr - 4 * fq - r;
;                         bool valid = !tile_off;
;                         if (D == 8) valid = valid && (dl < 0);
;                         if (D == 0) valid = valid && (dl >= 0);
;                         const float sv = valid ? st[x][t][r] : -1e30f; st[x][t][r] = sv; mx = fmaxf(mx, sv); }
;                 }
;                 mx = fmaxf(mx, __shfl_xor(mx, 16)); mx = fmaxf(mx, __shfl_xor(mx, 32)); mx = fmaxf(mx, sink);
.LBB0_278:
	s_lshl_b32 s37, s52, 2
	s_and_b32 s51, s37, 4
	v_add_u32_e32 v68, s51, v133
	v_ashrrev_i32_e32 v69, 31, v68
	v_lshl_add_u64 v[70:71], v[68:69], 2, s[0:1]
	global_load_dword v144, v[70:71], off
	v_lshlrev_b32_e32 v68, 6, v68
	v_ashrrev_i32_e32 v69, 31, v68
	v_lshl_add_u64 v[146:147], v[68:69], 1, v[138:139]
	ds_read_b128 v[68:71], v151
	ds_read_b128 v[72:75], v151 offset:64
	ds_read_b128 v[76:79], v151 offset:2304
	ds_read_b128 v[80:83], v151 offset:2368
	s_waitcnt vmcnt(1) lgkmcnt(3)
	v_mfma_f32_16x16x32_bf16 v[68:71], v[68:71], v[32:35], 0
	s_ashr_i32 s36, s52, 7
	s_bfe_u32 s50, s52, 0x60001
	s_ashr_i32 s37, s36, 31
	s_waitcnt lgkmcnt(2)
	v_mfma_f32_16x16x32_bf16 v[158:161], v[72:75], v[28:31], v[68:71]
	s_nop 2
	ds_read_b128 v[68:71], v151 offset:4608
	ds_read_b128 v[84:87], v151 offset:4672
	s_lshl_b32 s52, s50, 7
	s_lshl_b64 s[36:37], s[36:37], 13
	s_waitcnt lgkmcnt(3)
	v_mfma_f32_16x16x32_bf16 v[72:75], v[76:79], v[32:35], 0
	s_or_b32 s36, s36, s52
	s_cmp_lg_u32 s50, 0
	s_cselect_b64 s[60:61], -1, 0
	s_waitcnt lgkmcnt(2)
	v_mfma_f32_16x16x32_bf16 v[104:107], v[80:83], v[28:31], v[72:75]
	s_and_b64 s[50:51], s[60:61], s[38:39]
	s_and_b64 s[52:53], s[60:61], s[40:41]
	v_cndmask_b32_e64 v143, v197, v158, s[50:51]
	v_mfma_f32_16x16x32_bf16 v[72:75], v[76:79], v[40:43], 0
	v_cndmask_b32_e64 v157, v197, v159, s[52:53]
	s_and_b64 s[54:55], s[60:61], s[42:43]
	s_and_b64 s[56:57], s[60:61], s[44:45]
	v_mfma_f32_16x16x32_bf16 v[72:75], v[80:83], v[36:39], v[72:75]
	ds_read_b128 v[80:83], v151 offset:6912
	ds_read_b128 v[88:91], v151 offset:6976
	v_max3_f32 v145, v143, s78, v157
	v_cndmask_b32_e64 v158, v197, v160, s[54:55]
	s_waitcnt lgkmcnt(3)
	v_mfma_f32_16x16x32_bf16 v[76:79], v[68:71], v[32:35], 0
	v_cndmask_b32_e64 v159, v197, v161, s[56:57]
	v_max3_f32 v145, v145, v158, v159
	v_cndmask_b32_e64 v104, v197, v104, s[60:61]
	v_mfma_f32_16x16x32_bf16 v[68:71], v[68:71], v[40:43], 0
	v_cndmask_b32_e64 v105, v197, v105, s[60:61]
	v_max3_f32 v145, v145, v104, v105
	v_cndmask_b32_e64 v106, v197, v106, s[60:61]
	s_waitcnt lgkmcnt(2)
	v_mfma_f32_16x16x32_bf16 v[108:111], v[84:87], v[28:31], v[76:79]
	v_cndmask_b32_e64 v107, v197, v107, s[60:61]
	v_max3_f32 v145, v145, v106, v107
	s_or_b64 s[58:59], s[60:61], s[46:47]
	v_mfma_f32_16x16x32_bf16 v[76:79], v[84:87], v[36:39], v[68:71]
	s_nop 2
	ds_read_b128 v[68:71], v151 offset:9216
	ds_read_b128 v[84:87], v151 offset:9280
	v_cndmask_b32_e64 v108, v197, v108, s[60:61]
	v_cndmask_b32_e64 v109, v197, v109, s[60:61]
	s_waitcnt lgkmcnt(3)
	v_mfma_f32_16x16x32_bf16 v[92:95], v[80:83], v[32:35], 0
	v_max3_f32 v145, v145, v108, v109
	v_cndmask_b32_e64 v110, v197, v110, s[60:61]
	v_cndmask_b32_e64 v111, v197, v111, s[60:61]
	v_mfma_f32_16x16x32_bf16 v[80:83], v[80:83], v[40:43], 0
	v_max3_f32 v145, v145, v110, v111
	v_cndmask_b32_e64 v74, v197, v74, s[54:55]
	v_cndmask_b32_e64 v75, v197, v75, s[56:57]
	s_waitcnt lgkmcnt(2)
	v_mfma_f32_16x16x32_bf16 v[112:115], v[88:91], v[28:31], v[92:95]
	v_cndmask_b32_e64 v76, v197, v76, s[60:61]
	v_cndmask_b32_e64 v77, v197, v77, s[60:61]
	v_cndmask_b32_e64 v78, v197, v78, s[60:61]
	v_mfma_f32_16x16x32_bf16 v[80:83], v[88:91], v[36:39], v[80:83]
	ds_read_b128 v[88:91], v151 offset:11520
	ds_read_b128 v[92:95], v151 offset:11584
	s_nop 1
	v_cndmask_b32_e64 v160, v197, v112, s[60:61]
	v_cndmask_b32_e64 v161, v197, v113, s[60:61]
	s_waitcnt lgkmcnt(3)
	v_mfma_f32_16x16x32_bf16 v[96:99], v[68:71], v[32:35], 0
	v_max3_f32 v112, v145, v160, v161
	v_cndmask_b32_e64 v114, v197, v114, s[60:61]
	v_cndmask_b32_e64 v115, v197, v115, s[60:61]
	v_mfma_f32_16x16x32_bf16 v[68:71], v[68:71], v[40:43], 0
	v_max3_f32 v112, v112, v114, v115
	v_cndmask_b32_e64 v79, v197, v79, s[60:61]
	v_cndmask_b32_e64 v80, v197, v80, s[60:61]
	s_waitcnt lgkmcnt(2)
	v_mfma_f32_16x16x32_bf16 v[116:119], v[84:87], v[28:31], v[96:99]
	v_cndmask_b32_e64 v81, v197, v81, s[60:61]
	v_cndmask_b32_e64 v82, v197, v82, s[60:61]
	v_cndmask_b32_e64 v83, v197, v83, s[60:61]
	v_mfma_f32_16x16x32_bf16 v[84:87], v[84:87], v[36:39], v[68:71]
	s_nop 2
	ds_read_b128 v[68:71], v151 offset:13824
	ds_read_b128 v[96:99], v151 offset:13888
	v_cndmask_b32_e64 v116, v197, v116, s[58:59]
	v_cndmask_b32_e64 v117, v197, v117, s[58:59]
	s_waitcnt lgkmcnt(3)
	v_mfma_f32_16x16x32_bf16 v[100:103], v[88:91], v[32:35], 0
	v_max3_f32 v112, v112, v116, v117
	v_cndmask_b32_e64 v118, v197, v118, s[58:59]
	v_cndmask_b32_e64 v190, v197, v119, s[58:59]
	v_mfma_f32_16x16x32_bf16 v[88:91], v[88:91], v[40:43], 0
	v_max3_f32 v112, v112, v118, v190
	v_cndmask_b32_e64 v84, v197, v84, s[58:59]
	s_waitcnt lgkmcnt(2)
	v_mfma_f32_16x16x32_bf16 v[120:123], v[92:95], v[28:31], v[100:103]
	s_nop 2
	ds_read_b128 v[100:103], v151 offset:16128
	ds_read_b128 v[174:177], v151 offset:16192
	s_nop 2
	v_cndmask_b32_e64 v191, v197, v120, s[58:59]
	v_mfma_f32_16x16x32_bf16 v[88:91], v[92:95], v[36:39], v[88:91]
	v_cndmask_b32_e64 v199, v197, v121, s[58:59]
	v_max3_f32 v112, v112, v191, v199
	v_cndmask_b32_e64 v200, v197, v122, s[58:59]
	s_waitcnt lgkmcnt(3)
	v_mfma_f32_16x16x32_bf16 v[92:95], v[68:71], v[32:35], 0
	v_cndmask_b32_e64 v201, v197, v123, s[58:59]
	v_max3_f32 v112, v112, v200, v201
	v_mfma_f32_16x16x32_bf16 v[68:71], v[68:71], v[40:43], 0
	s_waitcnt lgkmcnt(2)
	v_mfma_f32_16x16x32_bf16 v[124:127], v[96:99], v[28:31], v[92:95]
	v_mfma_f32_16x16x32_bf16 v[92:95], v[96:99], v[36:39], v[68:71]
	s_nop 4
	ds_read_b128 v[68:71], v151 offset:18432
	ds_read_b128 v[178:181], v151 offset:18496
	v_cndmask_b32_e64 v202, v197, v124, s[58:59]
	v_cndmask_b32_e64 v203, v197, v125, s[58:59]
	s_waitcnt lgkmcnt(3)
; __device__ __forceinline__ void attn_phase(LAS unsigned char* lds, const bf16* PROJ, bf16* CONCAT, const float* sinks) {
;     ...
;             for (int x = 0; x < 2; ++x) {
;                 float mx = -1e30f;
; #pragma unroll
;                 for (int t = 0; t < 10; ++t) {
;                     const int D = x + 8 - t;
;                     if (D == 9 || D == -1) continue;
;                     const bool tile_off = firstblk && (kt0 + t < 8);
; #pragma unroll
;                     for (int r = 0; r < 4; ++r) { const int dl = fr - 4 * fq - r;
;                         bool valid = !tile_off;
;                         if (D == 8) valid = valid && (dl < 0);
;                         if (D == 0) valid = valid && (dl >= 0);
;                         const float sv = valid ? st[x][t][r] : -1e30f; st[x][t][r] = sv; mx = fmaxf(mx, sv); }
;                 }
;                 mx = fmaxf(mx, __shfl_xor(mx, 16)); mx = fmaxf(mx, __shfl_xor(mx, 32)); mx = fmaxf(mx, sink);
;                 const float mb = mx * LOG2E;
;                 float lsum = 0.f;
; #pragma unroll
;                 for (int t = 0; t < 10; ++t) {
;                     const int D = x + 8 - t;
;                     if (D == 9 || D == -1) { st[x][t] = (f32x4){0.f, 0.f, 0.f, 0.f}; continue; }
; #pragma unroll
;                     for (int r = 0; r < 4; ++r) { const float pe = __builtin_amdgcn_exp2f(st[x][t][r] * LOG2E - mb); st[x][t][r] = pe; lsum += pe; }
;                 }
;                 lsum += __shfl_xor(lsum, 16); lsum += __shfl_xor(lsum, 32); lsum += __builtin_amdgcn_exp2f(sink * LOG2E - mb);
;                 inv[x] = 1.0f / lsum;
	v_mfma_f32_16x16x32_bf16 v[96:99], v[100:103], v[32:35], 0
	v_max3_f32 v112, v112, v202, v203
	v_cndmask_b32_e64 v208, v197, v126, s[58:59]
	v_cndmask_b32_e64 v209, v197, v127, s[58:59]
	s_waitcnt lgkmcnt(1)
	v_mfma_f32_16x16x32_bf16 v[186:189], v[68:71], v[32:35], 0
	v_max3_f32 v112, v112, v208, v209
	v_mfma_f32_16x16x32_bf16 v[182:185], v[174:177], v[28:31], v[96:99]
	s_waitcnt lgkmcnt(0)
	v_mfma_f32_16x16x32_bf16 v[186:189], v[178:181], v[28:31], v[186:189]
	v_mfma_f32_16x16x32_bf16 v[96:99], v[100:103], v[40:43], 0
	s_nop 4
	v_cndmask_b32_e64 v182, v197, v182, s[58:59]
	v_cndmask_b32_e64 v183, v197, v183, s[58:59]
	v_max3_f32 v112, v112, v182, v183
	v_cndmask_b32_e64 v184, v197, v184, s[58:59]
	v_cndmask_b32_e64 v185, v197, v185, s[58:59]
	v_max3_f32 v112, v112, v184, v185
	v_cndmask_b32_e64 v186, v186, v197, s[38:39]
	v_cndmask_b32_e64 v187, v197, v187, s[48:49]
	v_max3_f32 v112, v112, v186, v187
	v_cndmask_b32_e64 v188, v188, v197, s[42:43]
	v_cndmask_b32_e64 v189, v189, v197, s[44:45]
	v_max3_f32 v112, v112, v188, v189
	ds_bpermute_b32 v113, v135, v112
	v_mfma_f32_16x16x32_bf16 v[96:99], v[174:177], v[36:39], v[96:99]
	ds_read_b128 v[100:103], v151 offset:20736
	ds_read_b128 v[174:177], v151 offset:20800
	s_waitcnt lgkmcnt(2)
	v_max_f32_e32 v113, v113, v113
	v_max_f32_e32 v112, v112, v113
	ds_bpermute_b32 v113, v148, v112
	s_waitcnt lgkmcnt(2)
	v_mfma_f32_16x16x32_bf16 v[100:103], v[100:103], v[40:43], 0
	v_cndmask_b32_e64 v210, v197, v99, s[58:59]
	s_waitcnt vmcnt(0) lgkmcnt(0)
	v_max3_f32 v145, v112, v113, v144
	v_pk_mul_f32 v[112:113], v[144:145], s[26:27] op_sel_hi:[1,0]
	v_mfma_f32_16x16x32_bf16 v[68:71], v[68:71], v[40:43], 0
	v_fma_f32 v119, v143, s26, -v113
	v_fma_f32 v120, v157, s26, -v113
	v_fma_f32 v104, v104, s26, -v113
	v_mfma_f32_16x16x32_bf16 v[100:103], v[174:177], v[36:39], v[100:103]
	v_exp_f32_e32 v174, v119
	v_exp_f32_e32 v175, v120
	v_fma_f32 v120, v158, s26, -v113
	v_exp_f32_e32 v176, v120
	v_fma_f32 v120, v159, s26, -v113
	v_exp_f32_e32 v177, v120
	v_mfma_f32_16x16x32_bf16 v[68:71], v[178:181], v[36:39], v[68:71]
	v_add_f32_e32 v119, 0, v174
	v_exp_f32_e32 v178, v104
	v_fma_f32 v105, v105, s26, -v113
	v_add_f32_e32 v119, v175, v119
	v_exp_f32_e32 v179, v105
	v_fma_f32 v105, v106, s26, -v113
	v_add_f32_e32 v119, v176, v119
	v_exp_f32_e32 v180, v105
	v_fma_f32 v105, v107, s26, -v113
	v_add_f32_e32 v119, v177, v119
	v_exp_f32_e32 v181, v105
	v_fma_f32 v105, v108, s26, -v113
	v_add_f32_e32 v104, v178, v119
	v_exp_f32_e32 v127, v105
	v_fma_f32 v105, v109, s26, -v113
	v_add_f32_e32 v104, v179, v104
	v_exp_f32_e32 v143, v105
	v_fma_f32 v105, v110, s26, -v113
	v_add_f32_e32 v104, v180, v104
	v_exp_f32_e32 v145, v105
	v_fma_f32 v105, v111, s26, -v113
	v_add_f32_e32 v104, v181, v104
	v_exp_f32_e32 v157, v105
	v_fma_f32 v105, v160, s26, -v113
	v_add_f32_e32 v104, v127, v104
	v_exp_f32_e32 v158, v105
	v_fma_f32 v105, v161, s26, -v113
	v_add_f32_e32 v104, v143, v104
	v_exp_f32_e32 v159, v105
	v_fma_f32 v105, v114, s26, -v113
	v_add_f32_e32 v104, v145, v104
	v_exp_f32_e32 v160, v105
	v_fma_f32 v105, v115, s26, -v113
	v_add_f32_e32 v104, v157, v104
	v_exp_f32_e32 v161, v105
	v_fma_f32 v105, v116, s26, -v113
	v_add_f32_e32 v104, v158, v104
	v_exp_f32_e32 v119, v105
	v_fma_f32 v105, v117, s26, -v113
	v_add_f32_e32 v104, v159, v104
	v_exp_f32_e32 v120, v105
	v_fma_f32 v105, v118, s26, -v113
	v_add_f32_e32 v104, v160, v104
	v_exp_f32_e32 v121, v105
	v_fma_f32 v105, v190, s26, -v113
	v_add_f32_e32 v104, v161, v104
	v_exp_f32_e32 v122, v105
	v_fma_f32 v105, v191, s26, -v113
	v_add_f32_e32 v104, v119, v104
	v_exp_f32_e32 v123, v105
	v_fma_f32 v105, v199, s26, -v113
	v_add_f32_e32 v104, v120, v104
	v_exp_f32_e32 v124, v105
	v_fma_f32 v105, v200, s26, -v113
	v_add_f32_e32 v104, v121, v104
	v_exp_f32_e32 v125, v105
	v_fma_f32 v105, v201, s26, -v113
	v_add_f32_e32 v104, v122, v104
	v_exp_f32_e32 v126, v105
	v_fma_f32 v105, v202, s26, -v113
	v_add_f32_e32 v104, v123, v104
	v_exp_f32_e32 v109, v105
	v_fma_f32 v105, v203, s26, -v113
	v_add_f32_e32 v104, v124, v104
	v_exp_f32_e32 v110, v105
	v_fma_f32 v105, v208, s26, -v113
	v_add_f32_e32 v104, v125, v104
	v_exp_f32_e32 v111, v105
	v_fma_f32 v105, v209, s26, -v113
	v_add_f32_e32 v104, v126, v104
	v_exp_f32_e32 v114, v105
	v_fma_f32 v105, v182, s26, -v113
	v_add_f32_e32 v104, v109, v104
	v_exp_f32_e32 v115, v105
	v_fma_f32 v105, v183, s26, -v113
	v_add_f32_e32 v104, v110, v104
	v_exp_f32_e32 v116, v105
	v_fma_f32 v105, v184, s26, -v113
	v_add_f32_e32 v104, v111, v104
	v_exp_f32_e32 v117, v105
	v_fma_f32 v105, v185, s26, -v113
	v_add_f32_e32 v104, v114, v104
	v_exp_f32_e32 v118, v105
	v_fma_f32 v105, v186, s26, -v113
	v_add_f32_e32 v104, v115, v104
	v_exp_f32_e32 v105, v105
	v_fma_f32 v106, v187, s26, -v113
	v_add_f32_e32 v104, v116, v104
	v_exp_f32_e32 v106, v106
	v_fma_f32 v107, v188, s26, -v113
	v_add_f32_e32 v104, v117, v104
	v_exp_f32_e32 v107, v107
	v_fma_f32 v108, v189, s26, -v113
	v_add_f32_e32 v104, v118, v104
	v_exp_f32_e32 v108, v108
	v_add_f32_e32 v104, v105, v104
	v_add_f32_e32 v104, v106, v104
	v_add_f32_e32 v104, v107, v104
	v_add_f32_e32 v104, v108, v104
	ds_bpermute_b32 v182, v135, v104
	v_sub_f32_e32 v113, v112, v113
	v_exp_f32_e32 v113, v113
	v_cndmask_b32_e64 v186, v197, v86, s[58:59]
	v_cndmask_b32_e64 v187, v197, v87, s[58:59]
	s_waitcnt lgkmcnt(0)
	v_add_f32_e32 v104, v104, v182
	ds_bpermute_b32 v182, v148, v104
	v_cndmask_b32_e64 v188, v197, v88, s[58:59]
	v_cndmask_b32_e64 v189, v197, v89, s[58:59]
	v_cndmask_b32_e64 v190, v197, v90, s[58:59]
	v_cndmask_b32_e64 v191, v197, v91, s[58:59]
	s_waitcnt lgkmcnt(0)
; __device__ __forceinline__ void attn_phase(LAS unsigned char* lds, const bf16* PROJ, bf16* CONCAT, const float* sinks) {
;     ...
;                 mx = fmaxf(mx, __shfl_xor(mx, 16)); mx = fmaxf(mx, __shfl_xor(mx, 32)); mx = fmaxf(mx, sink);
;                 const float mb = mx * LOG2E;
;                 float lsum = 0.f;
; #pragma unroll
;                 for (int t = 0; t < 10; ++t) {
;                     const int D = x + 8 - t;
;                     if (D == 9 || D == -1) { st[x][t] = (f32x4){0.f, 0.f, 0.f, 0.f}; continue; }
; #pragma unroll
;                     for (int r = 0; r < 4; ++r) { const float pe = __builtin_amdgcn_exp2f(st[x][t][r] * LOG2E - mb); st[x][t][r] = pe; lsum += pe; }
;                 }
;                 lsum += __shfl_xor(lsum, 16); lsum += __shfl_xor(lsum, 32); lsum += __builtin_amdgcn_exp2f(sink * LOG2E - mb);
;                 inv[x] = 1.0f / lsum;
	v_add_f32_e32 v104, v104, v182
	v_add_f32_e32 v104, v113, v104
	v_div_scale_f32 v113, s[70:71], v104, v104, 1.0
	v_rcp_f32_e32 v182, v113
	v_cndmask_b32_e64 v199, v197, v92, s[58:59]
	v_cndmask_b32_e64 v200, v197, v93, s[58:59]
	v_cndmask_b32_e64 v201, v197, v94, s[58:59]
	v_fma_f32 v183, -v113, v182, 1.0
	v_fmac_f32_e32 v182, v183, v182
	v_div_scale_f32 v183, vcc, 1.0, v104, 1.0
	v_mul_f32_e32 v184, v183, v182
	v_fma_f32 v185, -v113, v184, v183
	v_fmac_f32_e32 v184, v185, v182
	v_fma_f32 v113, -v113, v184, v183
	v_div_fmas_f32 v113, v113, v182, v184
	v_div_fixup_f32 v104, v113, v104, 1.0
	v_cndmask_b32_e64 v113, v197, v72, s[50:51]
	v_cndmask_b32_e64 v184, v197, v73, s[52:53]
	v_max3_f32 v72, v113, s78, v184
	v_max3_f32 v72, v72, v74, v75
	v_max3_f32 v72, v72, v76, v77
	v_max3_f32 v72, v72, v78, v79
	v_max3_f32 v72, v72, v80, v81
	v_max3_f32 v72, v72, v82, v83
	v_cndmask_b32_e64 v185, v197, v85, s[58:59]
	v_max3_f32 v72, v72, v84, v185
	v_max3_f32 v72, v72, v186, v187
	v_max3_f32 v72, v72, v188, v189
	v_max3_f32 v72, v72, v190, v191
	v_max3_f32 v72, v72, v199, v200
	v_cndmask_b32_e64 v202, v197, v95, s[58:59]
	v_max3_f32 v72, v72, v201, v202
	v_cndmask_b32_e64 v203, v197, v96, s[58:59]
	v_cndmask_b32_e64 v208, v197, v97, s[58:59]
	v_max3_f32 v72, v72, v203, v208
	v_cndmask_b32_e64 v209, v197, v98, s[58:59]
	v_max3_f32 v72, v72, v209, v210
	v_max3_f32 v72, v72, v68, v69
	v_max3_f32 v73, v72, v70, v71
	v_cndmask_b32_e64 v211, v100, v197, s[38:39]
	v_cndmask_b32_e64 v212, v197, v101, s[48:49]
	v_cndmask_b32_e64 v72, v102, v197, s[42:43]
	v_cndmask_b32_e64 v213, v103, v197, s[44:45]
	v_max3_f32 v73, v73, v211, v212
	v_max3_f32 v73, v73, v72, v213
	ds_bpermute_b32 v85, v135, v73
	s_waitcnt lgkmcnt(0)
	v_max_f32_e32 v85, v85, v85
	v_max_f32_e32 v73, v73, v85
	ds_bpermute_b32 v85, v148, v73
	s_waitcnt lgkmcnt(0)
	v_max3_f32 v73, v73, v85, v144
	v_pk_mul_f32 v[182:183], v[72:73], s[26:27] op_sel_hi:[1,0]
	s_nop 0
	v_fma_f32 v72, v113, s26, -v183
	v_exp_f32_e32 v101, v72
	v_fma_f32 v73, v184, s26, -v183
	v_exp_f32_e32 v102, v73
	v_fma_f32 v73, v74, s26, -v183
	v_exp_f32_e32 v103, v73
	v_fma_f32 v73, v75, s26, -v183
	v_exp_f32_e32 v113, v73
	v_fma_f32 v73, v76, s26, -v183
	v_add_f32_e32 v72, 0, v101
	v_exp_f32_e32 v93, v73
	v_fma_f32 v73, v77, s26, -v183
	v_add_f32_e32 v72, v102, v72
	v_exp_f32_e32 v94, v73
	v_fma_f32 v73, v78, s26, -v183
	v_add_f32_e32 v72, v103, v72
	v_exp_f32_e32 v95, v73
	v_fma_f32 v73, v79, s26, -v183
	v_add_f32_e32 v72, v113, v72
	v_exp_f32_e32 v96, v73
	v_fma_f32 v73, v80, s26, -v183
	v_add_f32_e32 v72, v93, v72
	v_exp_f32_e32 v97, v73
	v_fma_f32 v73, v81, s26, -v183
	v_add_f32_e32 v72, v94, v72
	v_exp_f32_e32 v98, v73
	v_fma_f32 v73, v82, s26, -v183
	v_add_f32_e32 v72, v95, v72
	v_exp_f32_e32 v99, v73
	v_fma_f32 v73, v83, s26, -v183
	v_add_f32_e32 v72, v96, v72
	v_exp_f32_e32 v100, v73
	v_fma_f32 v73, v84, s26, -v183
	v_add_f32_e32 v72, v97, v72
	v_exp_f32_e32 v85, v73
	v_fma_f32 v73, v185, s26, -v183
	v_add_f32_e32 v72, v98, v72
	v_exp_f32_e32 v86, v73
	v_fma_f32 v73, v186, s26, -v183
	v_add_f32_e32 v72, v99, v72
	v_exp_f32_e32 v87, v73
	v_fma_f32 v73, v187, s26, -v183
	v_add_f32_e32 v72, v100, v72
	v_exp_f32_e32 v88, v73
	v_fma_f32 v73, v188, s26, -v183
	v_add_f32_e32 v72, v85, v72
	v_exp_f32_e32 v89, v73
	v_fma_f32 v73, v189, s26, -v183
	v_add_f32_e32 v72, v86, v72
	v_exp_f32_e32 v90, v73
	v_fma_f32 v73, v190, s26, -v183
	v_add_f32_e32 v72, v87, v72
	v_exp_f32_e32 v91, v73
	v_fma_f32 v73, v191, s26, -v183
	v_add_f32_e32 v72, v88, v72
	v_exp_f32_e32 v92, v73
	v_fma_f32 v73, v199, s26, -v183
	v_add_f32_e32 v72, v89, v72
	v_exp_f32_e32 v77, v73
	v_fma_f32 v73, v200, s26, -v183
	v_add_f32_e32 v72, v90, v72
	v_exp_f32_e32 v78, v73
	v_fma_f32 v73, v201, s26, -v183
	v_add_f32_e32 v72, v91, v72
	v_exp_f32_e32 v79, v73
	v_fma_f32 v73, v202, s26, -v183
	v_add_f32_e32 v72, v92, v72
	v_exp_f32_e32 v80, v73
	v_fma_f32 v73, v203, s26, -v183
	v_add_f32_e32 v72, v77, v72
	v_exp_f32_e32 v81, v73
	v_fma_f32 v73, v208, s26, -v183
	v_add_f32_e32 v72, v78, v72
	v_exp_f32_e32 v82, v73
	v_fma_f32 v73, v209, s26, -v183
	v_add_f32_e32 v72, v79, v72
	v_exp_f32_e32 v83, v73
	v_fma_f32 v73, v210, s26, -v183
	v_add_f32_e32 v72, v80, v72
	v_exp_f32_e32 v84, v73
	v_add_f32_e32 v72, v81, v72
	v_add_f32_e32 v72, v82, v72
	v_add_f32_e32 v72, v83, v72
	v_fma_f32 v68, v68, s26, -v183
	v_add_f32_e32 v73, v84, v72
	v_exp_f32_e32 v72, v68
	v_fma_f32 v69, v69, s26, -v183
	v_exp_f32_e32 v69, v69
	v_fma_f32 v70, v70, s26, -v183
	v_exp_f32_e32 v70, v70
	v_fma_f32 v71, v71, s26, -v183
	v_add_f32_e32 v68, v72, v73
	v_exp_f32_e32 v71, v71
	v_fma_f32 v73, v211, s26, -v183
	v_exp_f32_e32 v73, v73
	v_fma_f32 v74, v212, s26, -v183
	v_add_f32_e32 v68, v69, v68
	v_exp_f32_e32 v74, v74
	v_sub_f32_e32 v75, v182, v183
	v_add_f32_e32 v68, v70, v68
	v_exp_f32_e32 v75, v75
	v_fma_f32 v76, v213, s26, -v183
	v_add_f32_e32 v68, v71, v68
	v_exp_f32_e32 v76, v76
	v_add_f32_e32 v68, v73, v68
	v_add_f32_e32 v68, v74, v68
	v_add_f32_e32 v68, v75, v68
	v_add_f32_e32 v68, v76, v68
	ds_bpermute_b32 v182, v135, v68
	s_waitcnt lgkmcnt(0)
	v_add_f32_e32 v68, v68, v182
	ds_bpermute_b32 v182, v148, v68
	s_waitcnt lgkmcnt(0)
; #define LAS __attribute__((address_space(3)))
; #define LAS __attribute__((address_space(3)))
; __device__ __forceinline__ unsigned pk2(float lo, float hi) { return pg8::cvt_pk_bf16(lo, hi); }
; #define ATT_LDV(s) do { _Pragma("unroll") for (int dt = 0; dt < 4; ++dt) { vlo[s][dt] = lds_tr_a(vp0 + (s) * 32 * 72 + 16 * dt); vhi[s][dt] = lds_tr_a(vp0 + (s) * 32 * 72 + 16 * 72 + 16 * dt); } } while (0)
; __device__ __forceinline__ void attn_phase(LAS unsigned char* lds, const bf16* PROJ, bf16* CONCAT, const float* sinks) {
;     ...
;                 inv[x] = 1.0f / lsum;
;             }
;             f32x4 ot[2][4];
; #pragma unroll
;             for (int x = 0; x < 2; ++x)
; #pragma unroll
;                 for (int dt = 0; dt < 4; ++dt) ot[x][dt] = (f32x4){0.f, 0.f, 0.f, 0.f};
;             const LAS bf16* vp0 = Vs + (16 * kt0 + 4 * fq + (fr >> 2)) * 72 + 4 * (fr & 3);
;             v2u vlo[5][4], vhi[5][4];
;     ...
; #pragma unroll
;             for (int s2 = 0; s2 < 5; ++s2) {
;                 ATT_LDV(s2);
;                 bf16x8 pf[2];
; #pragma unroll
;                 for (int x = 0; x < 2; ++x) { v4u pw; pw.x = pk2(st[x][2 * s2][0], st[x][2 * s2][1]); pw.y = pk2(st[x][2 * s2][2], st[x][2 * s2][3]);
;                     pw.z = pk2(st[x][2 * s2 + 1][0], st[x][2 * s2 + 1][1]); pw.w = pk2(st[x][2 * s2 + 1][2], st[x][2 * s2 + 1][3]); pf[x] = __builtin_bit_cast(bf16x8, pw); }
; #pragma unroll
;                 for (int dt = 0; dt < 4; ++dt) {
;                     const bf16x8 vf = __builtin_bit_cast(bf16x8, (v4u){vlo[s2][dt].x, vlo[s2][dt].y, vhi[s2][dt].x, vhi[s2][dt].y});
; #pragma unroll
;                     for (int x = 0; x < 2; ++x) ot[x][dt] = __builtin_amdgcn_mfma_f32_16x16x32_bf16(vf, pf[x], ot[x][dt], 0, 0, 0);
;                 }
;             }
	v_add_f32_e32 v68, v68, v182
	v_sub_f32_e32 v182, v112, v183
	v_exp_f32_e32 v182, v182
	s_nop 0
	v_add_f32_e32 v68, v182, v68
	v_div_scale_f32 v182, s[70:71], v68, v68, 1.0
	v_rcp_f32_e32 v183, v182
	s_nop 0
	v_fma_f32 v184, -v182, v183, 1.0
	v_fmac_f32_e32 v183, v184, v183
	v_div_scale_f32 v184, vcc, 1.0, v68, 1.0
	v_mul_f32_e32 v185, v184, v183
	v_fma_f32 v186, -v182, v185, v184
	v_fmac_f32_e32 v185, v186, v183
	v_fma_f32 v182, -v182, v185, v184
	v_div_fmas_f32 v182, v182, v183, v185
	v_div_fixup_f32 v68, v182, v68, 1.0
	ds_read_b64_tr_b16 v[182:183], v152 offset:36864
	ds_read_b64_tr_b16 v[186:187], v152 offset:36896
	ds_read_b64_tr_b16 v[184:185], v152 offset:39168
	ds_read_b64_tr_b16 v[188:189], v152 offset:39200
	ds_read_b64_tr_b16 v[200:201], v152 offset:36928
	ds_read_b64_tr_b16 v[202:203], v152 offset:39232
	ds_read_b64_tr_b16 v[208:209], v152 offset:36960
	ds_read_b64_tr_b16 v[210:211], v152 offset:39264
	v_cvt_pk_bf16_f32 v174, v174, v175
	v_cvt_pk_bf16_f32 v175, v176, v177
	v_cvt_pk_bf16_f32 v176, v178, v179
	v_cvt_pk_bf16_f32 v177, v180, v181
	v_cvt_pk_bf16_f32 v178, v1, v1
	v_cvt_pk_bf16_f32 v179, v1, v1
	v_cvt_pk_bf16_f32 v180, v101, v102
	v_cvt_pk_bf16_f32 v181, v103, v113
	s_waitcnt lgkmcnt(5)
	v_mfma_f32_16x16x32_bf16 v[212:215], v[182:185], v[174:177], 0
	v_mfma_f32_16x16x32_bf16 v[182:185], v[182:185], v[178:181], 0
	s_waitcnt lgkmcnt(4)
	v_mfma_f32_16x16x32_bf16 v[216:219], v[186:189], v[174:177], 0
	v_mfma_f32_16x16x32_bf16 v[186:189], v[186:189], v[178:181], 0
	s_waitcnt lgkmcnt(2)
	v_mfma_f32_16x16x32_bf16 v[220:223], v[200:203], v[174:177], 0
	v_mfma_f32_16x16x32_bf16 v[200:203], v[200:203], v[178:181], 0
	s_waitcnt lgkmcnt(0)
	v_mfma_f32_16x16x32_bf16 v[174:177], v[208:211], v[174:177], 0
	v_mfma_f32_16x16x32_bf16 v[178:181], v[208:211], v[178:181], 0
	ds_read_b64_tr_b16 v[208:209], v152 offset:41472
	ds_read_b64_tr_b16 v[224:225], v152 offset:41504
	ds_read_b64_tr_b16 v[210:211], v152 offset:43776
	ds_read_b64_tr_b16 v[226:227], v152 offset:43808
	ds_read_b64_tr_b16 v[228:229], v152 offset:41536
	ds_read_b64_tr_b16 v[230:231], v152 offset:43840
	ds_read_b64_tr_b16 v[232:233], v152 offset:41568
	ds_read_b64_tr_b16 v[234:235], v152 offset:43872
	v_cvt_pk_bf16_f32 v236, v127, v143
	v_cvt_pk_bf16_f32 v237, v145, v157
	v_cvt_pk_bf16_f32 v238, v158, v159
	v_cvt_pk_bf16_f32 v239, v160, v161
	v_cvt_pk_bf16_f32 v94, v93, v94
	v_cvt_pk_bf16_f32 v95, v95, v96
	v_cvt_pk_bf16_f32 v96, v97, v98
	v_cvt_pk_bf16_f32 v97, v99, v100
	v_mov_b32_e32 v143, v1
	s_waitcnt lgkmcnt(5)
	v_mfma_f32_16x16x32_bf16 v[98:101], v[208:211], v[236:239], v[212:215]
	v_mfma_f32_16x16x32_bf16 v[158:161], v[208:211], v[94:97], v[182:185]
	s_waitcnt lgkmcnt(4)
	v_mfma_f32_16x16x32_bf16 v[182:185], v[224:227], v[236:239], v[216:219]
	v_mfma_f32_16x16x32_bf16 v[186:189], v[224:227], v[94:97], v[186:189]
	s_waitcnt lgkmcnt(2)
	v_mfma_f32_16x16x32_bf16 v[208:211], v[228:231], v[236:239], v[220:223]
	v_mfma_f32_16x16x32_bf16 v[200:203], v[228:231], v[94:97], v[200:203]
	s_waitcnt lgkmcnt(0)
	v_mfma_f32_16x16x32_bf16 v[94:97], v[232:235], v[94:97], v[178:181]
	s_nop 2
	ds_read_b64_tr_b16 v[178:179], v152 offset:46080
	ds_read_b64_tr_b16 v[212:213], v152 offset:46112
	ds_read_b64_tr_b16 v[180:181], v152 offset:48384
	ds_read_b64_tr_b16 v[214:215], v152 offset:48416
	ds_read_b64_tr_b16 v[216:217], v152 offset:46144
	ds_read_b64_tr_b16 v[218:219], v152 offset:48448
	ds_read_b64_tr_b16 v[220:221], v152 offset:46176
	ds_read_b64_tr_b16 v[222:223], v152 offset:48480
	v_cvt_pk_bf16_f32 v120, v119, v120
	v_cvt_pk_bf16_f32 v121, v121, v122
	v_mfma_f32_16x16x32_bf16 v[174:177], v[232:235], v[236:239], v[174:177]
	v_cvt_pk_bf16_f32 v122, v123, v124
	v_cvt_pk_bf16_f32 v123, v125, v126
	v_cvt_pk_bf16_f32 v86, v85, v86
	v_cvt_pk_bf16_f32 v87, v87, v88
	v_cvt_pk_bf16_f32 v88, v89, v90
	v_cvt_pk_bf16_f32 v89, v91, v92
	s_waitcnt lgkmcnt(5)
	v_mfma_f32_16x16x32_bf16 v[90:93], v[178:181], v[120:123], v[98:101]
	v_mfma_f32_16x16x32_bf16 v[98:101], v[178:181], v[86:89], v[158:161]
	s_waitcnt lgkmcnt(4)
	v_mfma_f32_16x16x32_bf16 v[124:127], v[212:215], v[120:123], v[182:185]
	v_mfma_f32_16x16x32_bf16 v[158:161], v[212:215], v[86:89], v[186:189]
	s_waitcnt lgkmcnt(2)
	v_mfma_f32_16x16x32_bf16 v[178:181], v[216:219], v[120:123], v[208:211]
	v_mfma_f32_16x16x32_bf16 v[182:185], v[216:219], v[86:89], v[200:203]
	s_waitcnt lgkmcnt(0)
	v_mfma_f32_16x16x32_bf16 v[120:123], v[220:223], v[120:123], v[174:177]
	v_mfma_f32_16x16x32_bf16 v[86:89], v[220:223], v[86:89], v[94:97]
	s_nop 2
	ds_read_b64_tr_b16 v[94:95], v152 offset:50688
	ds_read_b64_tr_b16 v[174:175], v152 offset:50720
	ds_read_b64_tr_b16 v[96:97], v152 offset:52992
	ds_read_b64_tr_b16 v[176:177], v152 offset:53024
	ds_read_b64_tr_b16 v[186:187], v152 offset:50752
	ds_read_b64_tr_b16 v[188:189], v152 offset:53056
	ds_read_b64_tr_b16 v[200:201], v152 offset:50784
	ds_read_b64_tr_b16 v[202:203], v152 offset:53088
	v_cvt_pk_bf16_f32 v208, v109, v110
	v_cvt_pk_bf16_f32 v209, v111, v114
	v_cvt_pk_bf16_f32 v210, v115, v116
	v_cvt_pk_bf16_f32 v211, v117, v118
	v_cvt_pk_bf16_f32 v78, v77, v78
	v_cvt_pk_bf16_f32 v79, v79, v80
	v_cvt_pk_bf16_f32 v80, v81, v82
	v_cvt_pk_bf16_f32 v81, v83, v84
	s_waitcnt lgkmcnt(5)
	v_mfma_f32_16x16x32_bf16 v[82:85], v[94:97], v[208:211], v[90:93]
	v_mfma_f32_16x16x32_bf16 v[90:93], v[94:97], v[78:81], v[98:101]
	s_waitcnt lgkmcnt(4)
	v_mfma_f32_16x16x32_bf16 v[94:97], v[174:177], v[208:211], v[124:127]
	v_mfma_f32_16x16x32_bf16 v[98:101], v[174:177], v[78:81], v[158:161]
	s_waitcnt lgkmcnt(2)
	v_mfma_f32_16x16x32_bf16 v[114:117], v[186:189], v[208:211], v[178:181]
	v_mfma_f32_16x16x32_bf16 v[124:127], v[186:189], v[78:81], v[182:185]
	s_waitcnt lgkmcnt(0)
; #define LAS __attribute__((address_space(3)))
; __device__ __forceinline__ void attn_phase(LAS unsigned char* lds, const bf16* PROJ, bf16* CONCAT, const float* sinks) {
;     ...
;             const LAS bf16* kp0 = Ks + (16 * kt0 + fr) * 72 + 8 * fq;
;     ...
;             ATT_LDK(0);
; #pragma unroll
;             for (int t = 0; t < 10; ++t) {
;                 if (t + 1 < 10) ATT_LDK(t + 1);
; #pragma unroll
;                 for (int x = 0; x < 2; ++x) {
;                     if (x + 8 - t == 9 || x + 8 - t == -1) { st[x][t] = (f32x4){-1e30f, -1e30f, -1e30f, -1e30f}; continue; }
;                     f32x4 acc = (f32x4){0.f, 0.f, 0.f, 0.f};
;                     acc = __builtin_amdgcn_mfma_f32_16x16x32_bf16(kfr[t][0], qf[2 * p + x][0], acc, 0, 0, 0);
;                     acc = __builtin_amdgcn_mfma_f32_16x16x32_bf16(kfr[t][1], qf[2 * p + x][1], acc, 0, 0, 0);
;                     st[x][t] = acc;
;                 }
;             }
;     ...
;                 for (int x = 0; x < 2; ++x) { v4u pw; pw.x = pk2(st[x][2 * s2][0], st[x][2 * s2][1]); pw.y = pk2(st[x][2 * s2][2], st[x][2 * s2][3]);
;                     pw.z = pk2(st[x][2 * s2 + 1][0], st[x][2 * s2 + 1][1]); pw.w = pk2(st[x][2 * s2 + 1][2], st[x][2 * s2 + 1][3]); pf[x] = __builtin_bit_cast(bf16x8, pw); }
; #pragma unroll
;                 for (int dt = 0; dt < 4; ++dt) {
;                     const bf16x8 vf = __builtin_bit_cast(bf16x8, (v4u){vlo[s2][dt].x, vlo[s2][dt].y, vhi[s2][dt].x, vhi[s2][dt].y});
; #pragma unroll
;                     for (int x = 0; x < 2; ++x) ot[x][dt] = __builtin_amdgcn_mfma_f32_16x16x32_bf16(vf, pf[x], ot[x][dt], 0, 0, 0);
;                 }
;             }
;     ...
; #pragma unroll
;             for (int x = 0; x < 2; ++x) {
;                 LAS bf16* stg = (LAS bf16*)(lds + 73728) + (wave * 2 + x) * (16 * 72);
; #pragma unroll
;                 for (int dt = 0; dt < 4; ++dt) *(LAS v2u*)(stg + fr * 72 + 16 * dt + 4 * fq) = (v2u){pk2(ot[x][dt][0] * inv[x], ot[x][dt][1] * inv[x]), pk2(ot[x][dt][2] * inv[x], ot[x][dt][3] * inv[x])};
;                 bf16* op = CONCAT + (qrow0 - fr + 16 * (2 * p + x)) * DM + h * 64;
; #pragma unroll
;                 for (int i = 0; i < 2; ++i) { const int row = 8 * i + (lane >> 3), chn = lane & 7;
;                     *(v4u*)(op + (size_t)row * DM + chn * 8) = *(const LAS v4u*)(stg + row * 72 + chn * 8); }
;             }
	v_mfma_f32_16x16x32_bf16 v[78:81], v[200:203], v[78:81], v[86:89]
	s_nop 2
	ds_read_b64_tr_b16 v[86:87], v152 offset:55296
	ds_read_b64_tr_b16 v[158:159], v152 offset:55328
	ds_read_b64_tr_b16 v[88:89], v152 offset:57600
	ds_read_b64_tr_b16 v[160:161], v152 offset:57632
	ds_read_b64_tr_b16 v[174:175], v152 offset:55360
	ds_read_b64_tr_b16 v[176:177], v152 offset:57664
	ds_read_b64_tr_b16 v[178:179], v152 offset:55392
	ds_read_b64_tr_b16 v[180:181], v152 offset:57696
	v_cvt_pk_bf16_f32 v106, v105, v106
	v_cvt_pk_bf16_f32 v107, v107, v108
	v_cvt_pk_bf16_f32 v108, v1, v1
	v_cvt_pk_bf16_f32 v109, v1, v1
	v_cvt_pk_bf16_f32 v182, v72, v69
	v_cvt_pk_bf16_f32 v183, v70, v71
	v_cvt_pk_bf16_f32 v184, v73, v74
	v_mfma_f32_16x16x32_bf16 v[118:121], v[200:203], v[208:211], v[120:123]
	v_cvt_pk_bf16_f32 v185, v75, v76
	s_waitcnt lgkmcnt(5)
	v_mfma_f32_16x16x32_bf16 v[70:73], v[86:89], v[106:109], v[82:85]
	s_waitcnt lgkmcnt(4)
	v_mfma_f32_16x16x32_bf16 v[82:85], v[158:161], v[106:109], v[94:97]
	v_mfma_f32_16x16x32_bf16 v[74:77], v[86:89], v[182:185], v[90:93]
	s_nop 4
	v_mul_f32_e32 v69, v104, v70
	v_mul_f32_e32 v70, v104, v71
	v_mul_f32_e32 v71, v104, v73
	s_waitcnt lgkmcnt(2)
	v_mfma_f32_16x16x32_bf16 v[90:93], v[174:177], v[106:109], v[114:117]
	v_cvt_pk_bf16_f32 v70, v69, v70
	v_mul_f32_e32 v69, v104, v72
	v_cvt_pk_bf16_f32 v71, v69, v71
	v_mfma_f32_16x16x32_bf16 v[86:89], v[158:161], v[182:185], v[98:101]
	ds_write_b64 v150, v[70:71]
	v_mul_f32_e32 v69, v104, v82
	v_mul_f32_e32 v70, v104, v83
	s_waitcnt lgkmcnt(1)
	v_mfma_f32_16x16x32_bf16 v[98:101], v[178:181], v[106:109], v[118:121]
	v_mul_f32_e32 v71, v104, v85
	v_cvt_pk_bf16_f32 v70, v69, v70
	v_mul_f32_e32 v69, v104, v84
	v_cvt_pk_bf16_f32 v71, v69, v71
	ds_write_b64 v150, v[70:71] offset:32
	v_mul_f32_e32 v69, v104, v90
	v_mul_f32_e32 v70, v104, v91
	v_mul_f32_e32 v71, v104, v93
	v_cvt_pk_bf16_f32 v70, v69, v70
	v_mul_f32_e32 v69, v104, v92
	v_cvt_pk_bf16_f32 v71, v69, v71
	ds_write_b64 v150, v[70:71] offset:64
	v_mul_f32_e32 v69, v104, v98
	v_mul_f32_e32 v70, v104, v99
	v_mul_f32_e32 v71, v104, v101
	v_cvt_pk_bf16_f32 v70, v69, v70
	v_mul_f32_e32 v69, v104, v100
	v_cvt_pk_bf16_f32 v71, v69, v71
	ds_write_b64 v150, v[70:71] offset:96
	v_mov_b32_e32 v71, s37
	v_or_b32_e32 v70, s36, v134
	v_lshlrev_b64 v[70:71], 11, v[70:71]
	v_lshl_add_u64 v[114:115], v[146:147], 0, v[70:71]
	ds_read_b128 v[70:73], v153
	v_lshl_add_u64 v[82:83], v[114:115], 0, v[0:1]
	v_mfma_f32_16x16x32_bf16 v[94:97], v[174:177], v[182:185], v[124:127]
	v_mul_f32_e32 v69, v68, v74
	s_mov_b64 s[36:37], 0x8000
	s_waitcnt lgkmcnt(0)
	global_store_dwordx4 v[82:83], v[70:73], off
	ds_read_b128 v[70:73], v154
	v_lshl_add_u64 v[82:83], v[114:115], 0, v[142:143]
	v_mfma_f32_16x16x32_bf16 v[78:81], v[178:181], v[182:185], v[78:81]
	s_waitcnt lgkmcnt(0)
	global_store_dwordx4 v[82:83], v[70:73], off
	s_nop 1
	v_mul_f32_e32 v70, v68, v75
	v_cvt_pk_bf16_f32 v70, v69, v70
	v_mul_f32_e32 v69, v68, v76
	v_mul_f32_e32 v71, v68, v77
	v_cvt_pk_bf16_f32 v71, v69, v71
	ds_write_b64 v150, v[70:71] offset:2304
	v_mul_f32_e32 v69, v68, v86
	v_mul_f32_e32 v70, v68, v87
	v_cvt_pk_bf16_f32 v70, v69, v70
	v_mul_f32_e32 v69, v68, v88
	v_mul_f32_e32 v71, v68, v89
	v_cvt_pk_bf16_f32 v71, v69, v71
	ds_write_b64 v150, v[70:71] offset:2336
	v_mul_f32_e32 v69, v68, v94
	v_mul_f32_e32 v70, v68, v95
	v_cvt_pk_bf16_f32 v70, v69, v70
	v_mul_f32_e32 v69, v68, v96
	v_mul_f32_e32 v71, v68, v97
	v_cvt_pk_bf16_f32 v71, v69, v71
	ds_write_b64 v150, v[70:71] offset:2368
	v_mul_f32_e32 v69, v68, v78
	v_mul_f32_e32 v70, v68, v79
	v_cvt_pk_bf16_f32 v70, v69, v70
	v_mul_f32_e32 v69, v68, v80
	v_mul_f32_e32 v68, v68, v81
	v_cvt_pk_bf16_f32 v71, v69, v68
	ds_write_b64 v150, v[70:71] offset:2400
	ds_read_b128 v[68:71], v153 offset:2304
	v_lshl_add_u64 v[72:73], v[114:115], 0, s[36:37]
	v_lshl_add_u64 v[74:75], v[72:73], 0, v[0:1]
	v_lshl_add_u64 v[72:73], v[72:73], 0, v[142:143]
	s_waitcnt lgkmcnt(0)
	global_store_dwordx4 v[74:75], v[68:71], off
	ds_read_b128 v[68:71], v154 offset:2304
	s_waitcnt lgkmcnt(0)
	global_store_dwordx4 v[72:73], v[68:71], off
	ds_read_b128 v[68:71], v155
	ds_read_b128 v[72:75], v155 offset:64
	ds_read_b128 v[76:79], v155 offset:2304
	ds_read_b128 v[80:83], v155 offset:2368
	s_waitcnt lgkmcnt(3)
	v_mfma_f32_16x16x32_bf16 v[68:71], v[68:71], v[48:51], 0
	s_waitcnt lgkmcnt(2)
	v_mfma_f32_16x16x32_bf16 v[116:119], v[72:75], v[44:47], v[68:71]
	s_nop 5
	ds_read_b128 v[68:71], v155 offset:4608
	ds_read_b128 v[72:75], v155 offset:4672
	v_cndmask_b32_e64 v113, v197, v116, s[50:51]
	s_waitcnt lgkmcnt(3)
	v_mfma_f32_16x16x32_bf16 v[84:87], v[76:79], v[48:51], 0
	v_cndmask_b32_e64 v145, v197, v117, s[52:53]
	v_max3_f32 v116, v113, s78, v145
	v_cndmask_b32_e64 v118, v197, v118, s[54:55]
	v_mfma_f32_16x16x32_bf16 v[76:79], v[76:79], v[56:59], 0
	v_cndmask_b32_e64 v119, v197, v119, s[56:57]
	v_max3_f32 v116, v116, v118, v119
	s_waitcnt lgkmcnt(2)
	v_mfma_f32_16x16x32_bf16 v[120:123], v[80:83], v[44:47], v[84:87]
	v_mfma_f32_16x16x32_bf16 v[80:83], v[80:83], v[52:55], v[76:79]
	s_nop 2
	ds_read_b128 v[76:79], v155 offset:6912
	ds_read_b128 v[88:91], v155 offset:6976
	s_nop 1
	v_cndmask_b32_e64 v120, v197, v120, s[60:61]
	v_cndmask_b32_e64 v121, v197, v121, s[60:61]
	s_waitcnt lgkmcnt(3)
	v_mfma_f32_16x16x32_bf16 v[84:87], v[68:71], v[48:51], 0
	v_max3_f32 v116, v116, v120, v121
	v_cndmask_b32_e64 v122, v197, v122, s[60:61]
	v_cndmask_b32_e64 v123, v197, v123, s[60:61]
	v_mfma_f32_16x16x32_bf16 v[68:71], v[68:71], v[56:59], 0
	v_max3_f32 v116, v116, v122, v123
	v_cndmask_b32_e64 v82, v197, v82, s[54:55]
	v_cndmask_b32_e64 v83, v197, v83, s[56:57]
	s_waitcnt lgkmcnt(2)
; #define LAS __attribute__((address_space(3)))
; #define LAS __attribute__((address_space(3)))
; #define ATT_LDK(t) do { kfr[t][0] = *(const LAS bf16x8*)(kp0 + (t) * 16 * 72); kfr[t][1] = *(const LAS bf16x8*)(kp0 + (t) * 16 * 72 + 32); } while (0)
; __device__ __forceinline__ void attn_phase(LAS unsigned char* lds, const bf16* PROJ, bf16* CONCAT, const float* sinks) {
;     ...
;     const bool xmap = (gridDim.x == 256);
;     ...
;         for (int p = 0; p < 2; ++p) {
;             const int q16a = (wave & 1) * 4 + 2 * p, kt0 = q16a;
;             f32x4 st[2][10];
;             bf16x8 kfr[10][2];
;             const LAS bf16* kp0 = Ks + (16 * kt0 + fr) * 72 + 8 * fq;
;     ...
;             ATT_LDK(0);
; #pragma unroll
;             for (int t = 0; t < 10; ++t) {
;                 if (t + 1 < 10) ATT_LDK(t + 1);
; #pragma unroll
;                 for (int x = 0; x < 2; ++x) {
;                     if (x + 8 - t == 9 || x + 8 - t == -1) { st[x][t] = (f32x4){-1e30f, -1e30f, -1e30f, -1e30f}; continue; }
;                     f32x4 acc = (f32x4){0.f, 0.f, 0.f, 0.f};
;                     acc = __builtin_amdgcn_mfma_f32_16x16x32_bf16(kfr[t][0], qf[2 * p + x][0], acc, 0, 0, 0);
;                     acc = __builtin_amdgcn_mfma_f32_16x16x32_bf16(kfr[t][1], qf[2 * p + x][1], acc, 0, 0, 0);
;                     st[x][t] = acc;
;                 }
;             }
	v_mfma_f32_16x16x32_bf16 v[124:127], v[72:75], v[44:47], v[84:87]
	v_mfma_f32_16x16x32_bf16 v[84:87], v[72:75], v[52:55], v[68:71]
	s_nop 2
	ds_read_b128 v[68:71], v155 offset:9216
	ds_read_b128 v[72:75], v155 offset:9280
	s_nop 1
	v_cndmask_b32_e64 v124, v197, v124, s[58:59]
	v_cndmask_b32_e64 v125, v197, v125, s[58:59]
	s_waitcnt lgkmcnt(3)
	v_mfma_f32_16x16x32_bf16 v[92:95], v[76:79], v[48:51], 0
	v_max3_f32 v116, v116, v124, v125
	v_cndmask_b32_e64 v126, v197, v126, s[58:59]
	v_cndmask_b32_e64 v127, v197, v127, s[58:59]
	v_mfma_f32_16x16x32_bf16 v[76:79], v[76:79], v[56:59], 0
	v_max3_f32 v116, v116, v126, v127
	v_cndmask_b32_e64 v84, v197, v84, s[58:59]
	v_cndmask_b32_e64 v85, v197, v85, s[58:59]
	s_waitcnt lgkmcnt(2)
	v_mfma_f32_16x16x32_bf16 v[158:161], v[88:91], v[44:47], v[92:95]
	v_cndmask_b32_e64 v86, v197, v86, s[58:59]
	v_cndmask_b32_e64 v87, v197, v87, s[58:59]
	v_mfma_f32_16x16x32_bf16 v[88:91], v[88:91], v[52:55], v[76:79]
	s_nop 2
	ds_read_b128 v[76:79], v155 offset:11520
	ds_read_b128 v[96:99], v155 offset:11584
	v_cndmask_b32_e64 v146, v197, v158, s[58:59]
	s_nop 1
	v_cndmask_b32_e64 v88, v197, v88, s[58:59]
	s_waitcnt lgkmcnt(3)
	v_mfma_f32_16x16x32_bf16 v[92:95], v[68:71], v[48:51], 0
	v_cndmask_b32_e64 v89, v197, v89, s[58:59]
	v_cndmask_b32_e64 v90, v197, v90, s[58:59]
	v_cndmask_b32_e64 v91, v197, v91, s[58:59]
	v_mfma_f32_16x16x32_bf16 v[68:71], v[68:71], v[56:59], 0
	s_waitcnt lgkmcnt(2)
	v_mfma_f32_16x16x32_bf16 v[174:177], v[72:75], v[44:47], v[92:95]
	v_mfma_f32_16x16x32_bf16 v[92:95], v[72:75], v[52:55], v[68:71]
	s_nop 4
	ds_read_b128 v[68:71], v155 offset:13824
	ds_read_b128 v[72:75], v155 offset:13888
	v_cndmask_b32_e64 v190, v197, v177, s[58:59]
	v_cndmask_b32_e64 v92, v197, v92, s[58:59]
	s_waitcnt lgkmcnt(3)
	v_mfma_f32_16x16x32_bf16 v[100:103], v[76:79], v[48:51], 0
	v_cndmask_b32_e64 v93, v197, v93, s[58:59]
	v_cndmask_b32_e64 v94, v197, v94, s[58:59]
	v_cndmask_b32_e64 v95, v197, v95, s[58:59]
	v_mfma_f32_16x16x32_bf16 v[76:79], v[76:79], v[56:59], 0
	s_waitcnt lgkmcnt(2)
	v_mfma_f32_16x16x32_bf16 v[178:181], v[96:99], v[44:47], v[100:103]
	v_mfma_f32_16x16x32_bf16 v[96:99], v[96:99], v[52:55], v[76:79]
	s_nop 4
	ds_read_b128 v[76:79], v155 offset:16128
	ds_read_b128 v[100:103], v155 offset:16192
	ds_read_b128 v[182:185], v155 offset:18432
	ds_read_b128 v[186:189], v155 offset:18496
	v_cndmask_b32_e64 v191, v197, v178, s[58:59]
	s_waitcnt lgkmcnt(5)
	v_mfma_f32_16x16x32_bf16 v[104:107], v[68:71], v[48:51], 0
	v_cndmask_b32_e64 v199, v197, v179, s[58:59]
	v_mfma_f32_16x16x32_bf16 v[68:71], v[68:71], v[56:59], 0
	s_waitcnt lgkmcnt(4)
	v_mfma_f32_16x16x32_bf16 v[108:111], v[72:75], v[44:47], v[104:107]
	v_mfma_f32_16x16x32_bf16 v[68:71], v[72:75], v[52:55], v[68:71]
	s_waitcnt lgkmcnt(3)
	v_mfma_f32_16x16x32_bf16 v[72:75], v[76:79], v[48:51], 0
	s_waitcnt lgkmcnt(2)
	v_mfma_f32_16x16x32_bf16 v[104:107], v[100:103], v[44:47], v[72:75]
	v_mfma_f32_16x16x32_bf16 v[72:75], v[76:79], v[56:59], 0
	s_waitcnt lgkmcnt(1)
	v_mfma_f32_16x16x32_bf16 v[76:79], v[182:185], v[48:51], 0
	v_mfma_f32_16x16x32_bf16 v[72:75], v[100:103], v[52:55], v[72:75]
	ds_read_b128 v[100:103], v155 offset:20736
	ds_read_b128 v[200:203], v155 offset:20800
	s_waitcnt lgkmcnt(2)
	v_mfma_f32_16x16x32_bf16 v[208:211], v[186:189], v[44:47], v[76:79]
	v_mfma_f32_16x16x32_bf16 v[76:79], v[182:185], v[56:59], 0
	v_cndmask_b32_e64 v184, v197, v159, s[58:59]
	v_max3_f32 v116, v116, v146, v184
	v_cndmask_b32_e64 v185, v197, v160, s[58:59]
	v_mfma_f32_16x16x32_bf16 v[76:79], v[186:189], v[52:55], v[76:79]
	v_cndmask_b32_e64 v186, v197, v161, s[58:59]
	v_max3_f32 v116, v116, v185, v186
	v_cndmask_b32_e64 v187, v197, v174, s[58:59]
	s_waitcnt lgkmcnt(1)
	v_mfma_f32_16x16x32_bf16 v[100:103], v[100:103], v[56:59], 0
	v_cndmask_b32_e64 v188, v197, v175, s[58:59]
	v_max3_f32 v116, v116, v187, v188
	v_cndmask_b32_e64 v189, v197, v176, s[58:59]
	v_max3_f32 v116, v116, v189, v190
	s_waitcnt lgkmcnt(0)
	v_mfma_f32_16x16x32_bf16 v[100:103], v[200:203], v[52:55], v[100:103]
	s_andn2_b64 vcc, exec, s[64:65]
	s_cbranch_vccnz .Lattn_q_skip
	s_and_b32 s98, s17, 7
	s_lshl_b32 s98, s98, 7
	s_bfe_u32 s99, s17, 0x10009
	s_lshl_b32 s99, s99, 6
	s_or_b32 s98, s98, s99
	s_bfe_u32 s99, s17, 0x50003
	s_lshl_b32 s99, s99, 1
	s_or_b32 s98, s98, s99
	s_bfe_u32 s99, s17, 0x10008
	s_or_b32 s98, s98, s99
	s_and_b64 vcc, s[80:81], exec
	s_cselect_b32 s98, s98, s17
	s_ashr_i32 s100, s98, 7
	s_ashr_i32 s101, s100, 31
	s_lshl_b32 s99, s98, 6
	s_lshl_b64 s[100:101], s[100:101], 13
	s_and_b32 s99, s99, 0x1f80
	s_or_b32 s99, s100, s99
	v_or_b32_e32 v30, s99, v132
	s_lshl_b32 s99, s98, 2
	s_and_b32 s99, s99, 4
	v_add_lshl_u32 v28, s99, v133, 6
	v_ashrrev_i32_e32 v29, 31, v28
	v_lshl_add_u64 v[28:29], v[28:29], 1, v[140:141]
	v_mad_u64_u32 v[52:53], vcc, v30, s85, v[28:29]
	v_mad_i32_i24 v53, s101, v195, v53
	v_add_co_u32_e32 v36, vcc, 0xa000, v52
	global_load_dwordx4 v[32:35], v[52:53], off nt
	global_load_dwordx4 v[28:31], v[52:53], off offset:64 nt
	v_addc_co_u32_e32 v37, vcc, 0, v53, vcc
	v_add_co_u32_e32 v44, vcc, 0x14000, v52
	global_load_dwordx4 v[40:43], v[36:37], off nt
	s_nop 0
	global_load_dwordx4 v[36:39], v[36:37], off offset:64 nt
	v_addc_co_u32_e32 v45, vcc, 0, v53, vcc
	v_add_co_u32_e32 v52, vcc, 0x1e000, v52
	global_load_dwordx4 v[48:51], v[44:45], off nt
	s_nop 0
	global_load_dwordx4 v[44:47], v[44:45], off offset:64 nt
	v_addc_co_u32_e32 v53, vcc, 0, v53, vcc
	global_load_dwordx4 v[56:59], v[52:53], off nt
	s_nop 0
	global_load_dwordx4 v[52:55], v[52:53], off offset:64 nt

; #define LAS __attribute__((address_space(3)))
; #define LAS __attribute__((address_space(3)))
; template <int W> __device__ __forceinline__ void pool_load(const bf16* PROJ, int gi, int tt, int lane, v4u (&raw)[8]) {
;     const size_t t0 = (size_t)tt * 16; const int s0 = (int)(t0 & (SEQ - 1));
;     const int ch = lane & 15, rs = lane >> 4;
; #pragma unroll
;     for (int i = 0; i < 8; ++i) { const int r = rs + 4 * i;
;         raw[i] = (v4u){0u, 0u, 0u, 0u};
;         if (4 * i + 3 >= 17 - W) { if (s0 - 16 + r >= 0) raw[i] = *(const v4u*)(PROJ + (t0 - 16 + r) * INW + 768 + gi * 128 + ch * 8); } }
; template <int W> __device__ __forceinline__ void pool_group(const bf16* PROJ, bf16* CONCAT, LAS bf16* ust, int gi, int gw, int ngw, int lane) {
;     v4u ra[8], rb[8];
;     {
;         const int ch = lane & 15, rs = lane >> 4;
; #pragma unroll
;         for (int i = 0; i < 8; ++i) if (!(4 * i + 3 >= 17 - W)) *(LAS v4u*)(ust + (rs + 4 * i) * PL_US + ch * 8) = (v4u){0u, 0u, 0u, 0u};
;     }
;     int tt = gw;
;     if (tt < T / 16) pool_load<W>(PROJ, gi, tt, lane, ra);
;     while (tt < T / 16) {
;         const int tn = tt + ngw;
;         if (tn < T / 16) pool_load<W>(PROJ, gi, tn, lane, rb);
;         pool_compute<W>(CONCAT, ust, gi, tt, lane, ra);
;         tt = tn;
;         if (tt >= T / 16) break;
;         const int tn2 = tt + ngw;
;         if (tn2 < T / 16) pool_load<W>(PROJ, gi, tn2, lane, ra);
;         pool_compute<W>(CONCAT, ust, gi, tt, lane, rb);
;         tt = tn2;
;     }
; }
; __device__ __forceinline__ void pool_phase(LAS unsigned char* lds, const bf16* PROJ, bf16* CONCAT) {
;     int tid_ = threadIdx.x; asm volatile("" : "+v"(tid_)); const int tid = tid_, lane = tid & 63, wave = tid >> 6;
;     LAS bf16* ust = (LAS bf16*)(lds + wave * 8704);
;     __syncthreads();
; #pragma unroll 1
;     for (int gi = 0; gi < 4; ++gi) {
;         const int gw = blockIdx.x * 8 + wave, ngw = gridDim.x * 8;
;         if (gi == 0) pool_group<2>(PROJ, CONCAT, ust, gi, gw, ngw, lane);
;         else if (gi == 1) pool_group<4>(PROJ, CONCAT, ust, gi, gw, ngw, lane);
;         else if (gi == 2) pool_group<8>(PROJ, CONCAT, ust, gi, gw, ngw, lane);
;         else pool_group<16>(PROJ, CONCAT, ust, gi, gw, ngw, lane);
;     }
.LBB0_280:
	v_mov_b32_e32 v12, v192
	s_movk_i32 s0, 0x2200
	v_ashrrev_i32_e32 v0, 6, v12
	v_mul_lo_u32 v2, v0, s0
	v_readlane_b32 s0, v246, 47
	s_cmpk_eq_i32 s96, 0x100
	s_cbranch_scc0 .Lpool_map_skip
	s_and_b32 s100, s2, 7
	s_lshl_b32 s100, s100, 9
	s_lshr_b32 s101, s2, 3
	s_lshl_b32 s101, s101, 3
	s_add_i32 s0, s100, s101
	s_movk_i32 s84, 0x100
	s_add_i32 s79, s100, 0x200
	s_add_i32 s31, s100, 0x1ff
.Lpool_map_skip:
	v_bfe_u32 v68, v12, 4, 2
	v_add_u32_e32 v13, 0, v2
	v_add_u32_e32 v66, s0, v0
	v_ashrrev_i32_e32 v67, 31, v66
	v_lshlrev_b32_e32 v0, 4, v12
	v_lshlrev_b64 v[4:5], 4, v[66:67]
	v_and_b32_e32 v2, 0xf0, v0
	v_and_b32_e32 v0, 0x1ff0, v4
	v_lshl_add_u64 v[4:5], v[4:5], 0, -16
	v_or_b32_e32 v70, 8, v68
	v_sub_u32_e32 v15, 15, v0
	v_or_b32_e32 v0, v4, v70
	v_mov_b64_e32 v[6:7], s[74:75]
	v_mad_u64_u32 v[8:9], s[0:1], v0, s85, v[6:7]
	v_or_b32_e32 v74, 12, v68
	v_mad_i32_i24 v9, v5, s85, v9
	v_mov_b32_e32 v3, v1
	v_or_b32_e32 v0, v4, v74
	v_lshl_add_u64 v[72:73], v[8:9], 0, v[2:3]
	v_mad_u64_u32 v[8:9], s[0:1], v0, s85, v[6:7]
	v_mad_i32_i24 v9, v5, s85, v9
	v_or_b32_e32 v0, 16, v68
	v_lshl_add_u64 v[76:77], v[8:9], 0, v[2:3]
	v_lshl_add_u64 v[8:9], v[4:5], 0, v[0:1]
	v_mad_u64_u32 v[10:11], s[0:1], v8, s85, v[6:7]
	v_or_b32_e32 v80, 20, v68
	v_mov_b32_e32 v81, v1
	v_mad_i32_i24 v11, v9, s85, v11
	v_lshl_add_u64 v[8:9], v[4:5], 0, v[80:81]
	v_lshl_add_u64 v[78:79], v[10:11], 0, v[2:3]
	v_mad_u64_u32 v[10:11], s[0:1], v8, s85, v[6:7]
	v_or_b32_e32 v84, 24, v68
	v_mov_b32_e32 v85, v1
	v_mad_i32_i24 v11, v9, s85, v11
	v_lshl_add_u64 v[8:9], v[4:5], 0, v[84:85]
	v_lshl_add_u64 v[82:83], v[10:11], 0, v[2:3]
	v_mad_u64_u32 v[10:11], s[0:1], v8, s85, v[6:7]
	v_or_b32_e32 v88, 28, v68
	v_mov_b32_e32 v89, v1
	v_mad_i32_i24 v11, v9, s85, v11
	v_lshl_add_u64 v[8:9], v[4:5], 0, v[88:89]
	v_lshl_add_u64 v[86:87], v[10:11], 0, v[2:3]
	v_mad_u64_u32 v[10:11], s[0:1], v8, s85, v[6:7]
	v_mad_i32_i24 v11, v9, s85, v11
	v_and_b32_e32 v67, 15, v12
	v_lshlrev_b32_e32 v93, 3, v68
	v_lshl_add_u64 v[90:91], v[10:11], 0, v[2:3]
	v_sub_u32_e32 v10, v93, v67
	v_add_u32_e32 v11, -9, v10
	v_cmp_gt_u32_e32 vcc, 8, v11
	v_and_b32_e32 v17, -8, v10
	v_add_u32_e32 v18, -7, v10
	v_cndmask_b32_e64 v112, 0, 1.0, vcc
	v_cmp_eq_u32_e32 vcc, 8, v17
	v_add_u32_e32 v20, -6, v10
	v_add_u32_e32 v22, -5, v10
	v_cndmask_b32_e64 v113, 0, 1.0, vcc
	v_cmp_gt_u32_e32 vcc, 8, v18
	v_add_u32_e32 v23, -4, v10
	v_add_u32_e32 v24, -3, v10
	v_cndmask_b32_e64 v114, 0, 1.0, vcc
	v_cmp_gt_u32_e32 vcc, 8, v20
	v_add_u32_e32 v25, -2, v10
	v_lshlrev_b32_e32 v26, 3, v12
	v_cndmask_b32_e64 v115, 0, 1.0, vcc
	v_cmp_gt_u32_e32 vcc, 8, v22
	v_lshlrev_b32_e32 v8, 4, v67
	v_and_b32_e32 v26, 24, v26
	v_cndmask_b32_e64 v116, 0, 1.0, vcc
	v_cmp_gt_u32_e32 vcc, 8, v23
	s_movk_i32 s0, 0x110
	v_add_u32_e32 v69, v13, v2
	v_cndmask_b32_e64 v117, 0, 1.0, vcc
	v_cmp_gt_u32_e32 vcc, 8, v24
	v_add_u32_e32 v75, v13, v8
	v_mad_u32_u24 v121, v67, s0, v13
	v_cndmask_b32_e64 v118, 0, 1.0, vcc
	v_cmp_gt_u32_e32 vcc, 8, v25
	v_bfe_u32 v25, v12, 2, 2
	v_or_b32_e32 v25, v93, v25
	v_mul_u32_u24_e32 v25, 0x110, v25
	v_add3_u32 v120, v13, v25, v26
	v_lshlrev_b32_e32 v13, 8, v67
	v_lshrrev_b32_e32 v14, 4, v12
	v_sub_u32_e32 v122, v121, v13
	v_add_u32_e32 v13, -13, v10
	v_cndmask_b32_e64 v119, 0, 1.0, vcc
	v_bitop3_b32 v124, v14, 3, v14 bitop3:0xc
	v_cmp_gt_u32_e32 vcc, 4, v13
	v_and_b32_e32 v14, -4, v10
	v_add_u32_e32 v25, -11, v10
	v_cndmask_b32_e64 v125, 0, 1.0, vcc
	v_cmp_eq_u32_e32 vcc, 12, v14
	v_add_u32_e32 v26, -10, v10
	v_or_b32_e32 v92, 4, v68
	v_cndmask_b32_e64 v126, 0, 1.0, vcc
	v_cmp_gt_u32_e32 vcc, 4, v25
	v_add_u32_e32 v9, -16, v93
	v_add_u32_e32 v16, -15, v93
	v_cndmask_b32_e64 v127, 0, 1.0, vcc
	v_cmp_gt_u32_e32 vcc, 4, v26
	v_add_u32_e32 v17, -14, v93
	v_add_u32_e32 v19, -13, v93
	v_cndmask_b32_e64 v128, 0, 1.0, vcc
	v_cmp_gt_u32_e32 vcc, 4, v11
	v_add_u32_e32 v21, -12, v93
	v_add_u32_e32 v22, -11, v93
	v_cndmask_b32_e64 v129, 0, 1.0, vcc
	v_cmp_eq_u32_e32 vcc, 8, v14
	v_add_u32_e32 v14, -15, v10
	v_and_b32_e32 v10, -2, v10
	v_cndmask_b32_e64 v130, 0, 1.0, vcc
	v_cmp_gt_u32_e32 vcc, 4, v18
	v_add_u32_e32 v23, -10, v93
	v_add_u32_e32 v24, -9, v93
	v_cndmask_b32_e64 v131, 0, 1.0, vcc
	v_cmp_gt_u32_e32 vcc, 4, v20
	v_cmp_eq_u32_e64 s[44:45], v9, v67
	v_mul_u32_u24_e32 v71, 0x110, v68
	v_cndmask_b32_e64 v132, 0, 1.0, vcc
	v_cmp_gt_u32_e32 vcc, 2, v14
	v_cmp_gt_i32_e64 s[38:39], s79, v66
	v_cmp_gt_i32_e64 s[40:41], v70, v15
	v_cndmask_b32_e64 v133, 0, 1.0, vcc
	v_cmp_eq_u32_e32 vcc, 14, v10
	v_cmp_gt_i32_e64 s[42:43], v74, v15
	v_cmp_eq_u32_e64 s[46:47], v16, v67
	v_cndmask_b32_e64 v134, 0, 1.0, vcc
	v_cmp_gt_u32_e32 vcc, 2, v13
	v_cmp_eq_u32_e64 s[48:49], v17, v67
	v_cmp_eq_u32_e64 s[50:51], v19, v67
	v_cndmask_b32_e64 v135, 0, 1.0, vcc
	v_cmp_eq_u32_e32 vcc, 12, v10
	v_cmp_eq_u32_e64 s[52:53], v21, v67
	v_cmp_eq_u32_e64 s[54:55], v22, v67
	v_cndmask_b32_e64 v136, 0, 1.0, vcc
	v_cmp_gt_u32_e32 vcc, 2, v25
	v_cmp_eq_u32_e64 s[56:57], v23, v67
	v_cmp_eq_u32_e64 s[58:59], v24, v67
	v_cndmask_b32_e64 v137, 0, 1.0, vcc
	v_cmp_eq_u32_e32 vcc, 10, v10
	v_mul_u32_u24_e32 v123, 0x110, v92
	v_cmp_gt_i32_e64 s[60:61], v68, v15
	v_cndmask_b32_e64 v138, 0, 1.0, vcc
	v_cmp_gt_u32_e32 vcc, 2, v11
	v_cmp_gt_i32_e64 s[62:63], v92, v15
	v_lshl_add_u64 v[98:99], s[74:75], 0, v[2:3]
	v_cndmask_b32_e64 v139, 0, 1.0, vcc
	v_cmp_eq_u32_e32 vcc, 8, v10
	v_or_b32_e32 v10, v4, v68
	v_or_b32_e32 v4, v4, v92
	v_mad_u64_u32 v[10:11], s[0:1], v10, s85, v[6:7]
	v_mad_u64_u32 v[6:7], s[0:1], v4, s85, v[6:7]
	v_bitop3_b32 v4, v12, 15, v12 bitop3:0xc
	v_mad_i32_i24 v11, v5, s85, v11
	v_mad_i32_i24 v7, v5, s85, v7
	v_add_u32_e32 v5, v9, v4
	v_cndmask_b32_e64 v140, 0, 1.0, vcc
	v_cmp_gt_u32_e32 vcc, 16, v5
	v_add_u32_e32 v5, v16, v4
	v_mov_b32_e32 v9, v1
	v_cndmask_b32_e64 v141, 0, 1.0, vcc
	v_cmp_gt_u32_e32 vcc, 16, v5
	v_add_u32_e32 v5, v17, v4
	v_lshl_add_u64 v[94:95], v[10:11], 0, v[2:3]
	v_cndmask_b32_e64 v142, 0, 1.0, vcc
	v_cmp_gt_u32_e32 vcc, 16, v5
	v_add_u32_e32 v5, v19, v4
	v_lshl_add_u64 v[96:97], v[6:7], 0, v[2:3]
	v_cndmask_b32_e64 v143, 0, 1.0, vcc
	v_cmp_gt_u32_e32 vcc, 16, v5
	v_add_u32_e32 v5, v21, v4
	v_lshl_add_u64 v[100:101], s[24:25], 0, v[8:9]
	v_cndmask_b32_e64 v144, 0, 1.0, vcc
	v_cmp_gt_u32_e32 vcc, 16, v5
	v_add_u32_e32 v5, v22, v4
	s_mov_b32 s23, 0
	v_cndmask_b32_e64 v145, 0, 1.0, vcc
	v_cmp_gt_u32_e32 vcc, 16, v5
	v_add_u32_e32 v5, v23, v4
	v_add_u32_e32 v4, v24, v4
	v_cndmask_b32_e64 v146, 0, 1.0, vcc
	v_cmp_gt_u32_e32 vcc, 16, v5
	s_barrier
	s_nop 0
	v_cndmask_b32_e64 v147, 0, 1.0, vcc
	v_cmp_gt_u32_e32 vcc, 16, v4
	s_nop 1
	v_cndmask_b32_e64 v148, 0, 1.0, vcc
	s_branch .LBB0_283

; __device__ __forceinline__ unsigned xb_ld(unsigned* p)              { return __hip_atomic_load(p, __ATOMIC_RELAXED, __HIP_MEMORY_SCOPE_AGENT); }
; __device__ __forceinline__ unsigned xb_add(unsigned* p, unsigned v) { return __hip_atomic_fetch_add(p, v, __ATOMIC_RELAXED, __HIP_MEMORY_SCOPE_AGENT); }
; #define XB_SPIN(cond, bar) do { unsigned _sp = 0; while (cond) { __builtin_amdgcn_s_sleep(1); \
;     if ((++_sp & 255u) == 0u) { if (xb_ld(&(bar)[XB_TMO])) break; if (_sp > XB_SPIN_CAP) { atomicAdd(&(bar)[XB_TMO], 1u); break; } } } } while (0)
; __device__ __forceinline__ void xcd_barrier(const XcdBarrier& b) {
;     asm volatile("s_waitcnt vmcnt(0)" ::: "memory");
;     __syncthreads();
;     if (threadIdx.x == 0) {
;         unsigned* bar = b.bar;
;         __builtin_amdgcn_s_waitcnt(0);
;         unsigned nloc = b.st[0], nx = b.st[1];
;         if (nloc == 0u) { xcd_barrier_complete(bar, b.x, nloc, nx); b.st[0] = nloc; b.st[1] = nx; }
;         const unsigned old = xb_add(&bar[XB_XSUB(b.x)], 1u);
;         const unsigned gen = old / nloc;
;         if (old + 1u == (gen + 1u) * nloc) {
;             __builtin_amdgcn_fence(__ATOMIC_RELEASE, "agent");
;             asm volatile("s_waitcnt vmcnt(0)" ::: "memory");
;             const unsigned og = xb_add(&bar[XB_TOP], 1u);
;             const unsigned tg = og / nx;
;             if (og + 1u == (tg + 1u) * nx) xb_add(&bar[XB_TOPGEN], 1u);
;             else XB_SPIN(xb_ld(&bar[XB_TOPGEN]) == tg, bar);
;             __builtin_amdgcn_fence(__ATOMIC_ACQUIRE, "agent");
;             xb_add(&bar[XB_XGEN(b.x)], 1u);
;             asm volatile("s_waitcnt vmcnt(0)" ::: "memory");
;         } else {
;             XB_SPIN(xb_ld(&bar[XB_XGEN(b.x)]) == gen, bar);
.LBB0_409:
	s_or_b64 exec, exec, s[38:39]
	s_waitcnt vmcnt(0)
	s_waitcnt vmcnt(0)
.LBB0_410:
	s_andn2_saveexec_b64 s[16:17], s[36:37]
	s_cbranch_execz .LBB0_430
	v_readfirstlane_b32 s100, v247
	s_nop 3
	s_cmp_eq_u32 s100, 0
	s_cbranch_scc1 .Lxb_global_4
	v_readlane_b32 s100, v245, 18
	v_readlane_b32 s101, v245, 19
	v_mov_b32_e32 v251, 0
	v_mov_b32_e32 v250, 1
	s_nop 4
	global_atomic_add v251, v250, s[100:101]
	s_waitcnt vmcnt(1)
	s_branch .LBB0_430

;     __device__ bool next(int i, Unit& u) const { if (hot) { if (i >= rounds) return false; u.pm = (c % 8) * 2 + ((c / 8) & 1); u.pn = ((c / 8) >> 1) & 3; return true; } return so.next(i, u); }
;     __host__ __device__ bool next(int i, Unit& u) const {
;         const long L = (long)i * G + c; if (L >= nwg) return false;
;         int wgid = (int)L; { const int q = nwg / NXCD, r = nwg % NXCD, xcd = wgid % NXCD, off = wgid / NXCD; wgid = (xcd < r ? xcd * (q + 1) : r * (q + 1) + (xcd - r) * q) + off; }
;         const int nig = WGM * nN, gid = wgid / nig, fm = gid * WGM, gsz = (nM - fm) < WGM ? (nM - fm) : WGM;
;         u.pm = fm + ((wgid % nig) % gsz); u.pn = (wgid % nig) / gsz; if (rev) u.pm = nM - 1 - u.pm; return true;
.LBB0_650:
	s_ashr_i32 s16, s36, 3
	s_add_i32 s16, s44, s16
	s_ashr_i32 s17, s16, 31
	s_lshr_b32 s17, s17, 28
	s_add_i32 s17, s16, s17
	s_ashr_i32 s36, s17, 4
	s_lshl_b32 s36, s36, 2
	s_sub_i32 s37, 0x100, s36
	s_min_i32 s37, s37, 4
	s_abs_i32 s44, s37
	v_cvt_f32_u32_e32 v2, s44
	s_sub_i32 s50, 0, s44
	s_and_b32 s17, s17, -16
	s_sub_i32 s16, s16, s17
	v_rcp_iflag_f32_e32 v2, v2
	s_abs_i32 s17, s16
	s_xor_b32 s45, s16, s37
	s_ashr_i32 s45, s45, 31
	v_mul_f32_e32 v2, 0x4f7ffffe, v2
	v_cvt_u32_f32_e32 v2, v2
	s_nop 0
	v_readfirstlane_b32 s51, v2
	s_mul_i32 s50, s50, s51
	s_mul_hi_u32 s50, s51, s50
	s_add_i32 s51, s51, s50
	s_mul_hi_u32 s50, s17, s51
	s_mul_i32 s51, s50, s44
	s_sub_i32 s17, s17, s51
	s_add_i32 s52, s50, 1
	s_sub_i32 s51, s17, s44
	s_cmp_ge_u32 s17, s44
	s_cselect_b32 s50, s52, s50
	s_cselect_b32 s17, s51, s17
	s_add_i32 s51, s50, 1
	s_cmp_ge_u32 s17, s44
	s_cselect_b32 s17, s51, s50
	s_xor_b32 s17, s17, s45
	s_sub_i32 s63, s17, s45
	s_mul_i32 s17, s63, s37
	s_sub_i32 s16, s16, s17
	s_add_i32 s16, s16, s36
	s_and_b32 s100, s2, 7
	s_lshl_b32 s100, s100, 6
	s_add_i32 s100, s100, 31
	s_cmpk_eq_i32 s96, 0x100
	s_cselect_b32 s100, s100, 0xff
	s_sub_i32 s64, s100, s16

; __device__ __forceinline__ void rowwise_phase(const Args& a, LAS unsigned char* lds, bool from_partials, bool has_y, bool has_h, bool xin_bf, int xout_mode, ...
;     ...
;     for (int tile = blockIdx.x; tile < T / 256; tile += gridDim.x) {
;         const int b = tile / (SEQ / 256);
;         __syncthreads();
;         for (int col = tid; col < DM; col += 512) {
;             if (from_partials) {
;                 if (has_y) vec[col] = mod_val(a, l_y, b, gate_idx, col) * g_post[col];
;                 if (has_h) { vec[DM + col] = g_pre[col] * (1.0f + mod_val(a, l_h, b, scale_idx, col)); vec[2 * DM + col] = mod_val(a, l_h, b, shift_idx, col); }
;             } else {
;                 if (has_y) vec[col] = mod_fin(a, l_y, b, gate_idx, col) * g_post[col];
;                 if (has_h) { vec[DM + col] = g_pre[col] * (1.0f + mod_fin(a, l_h, b, scale_idx, col)); vec[2 * DM + col] = mod_fin(a, l_h, b, shift_idx, col); }
;             }
;         }
;         __syncthreads();
; __global__ void __launch_bounds__(512, 2) fwd_kernel(Args a) {
;     ...
;         for (int rep = 0; rep < REP_R; ++rep) rowwise_phase(a, lds, false, true, more, true, more ? 2 : 1, XA, MIX, a.out, XB, H, l, 5, a.g_post_ffn + l * DM, l + 1, 0, 1, a.g_pre_mix + (more ? (l + 1) * DM : 0));
.LBB0_717:
	s_and_b64 s[0:1], s[18:19], exec
	s_movk_i32 s0, 0x400
	v_ashrrev_i32_e32 v3, 4, v2
	v_cmp_gt_i32_e64 s[36:37], s0, v2
	v_and_b32_e32 v4, -4, v3
	s_movk_i32 s0, 0x100
	v_readlane_b32 s40, v244, 21
	v_cmp_gt_i32_e64 s[38:39], s0, v4
	s_mul_i32 s0, s40, 0x30000
	v_readlane_b32 s17, v244, 15
	s_cselect_b32 s16, 0x1000, 0
	v_readlane_b32 s41, v244, 22
	s_mul_hi_u32 s1, s40, 0x30000
	v_ashrrev_i32_e32 v3, 31, v2
	s_add_u32 s0, s17, s0
	v_readlane_b32 s17, v244, 16
	v_and_b32_e32 v0, 63, v2
	v_add_u32_e32 v135, 0xfffffe00, v2
	v_lshl_add_u32 v136, v2, 2, 0
	s_mov_b32 s41, s77
	v_lshlrev_b64 v[2:3], 2, v[2:3]
	s_addc_u32 s1, s17, s1
	v_lshl_add_u64 v[74:75], s[0:1], 0, v[2:3]
	s_lshl_b64 s[0:1], s[40:41], 12
	v_readlane_b32 s40, v246, 11
	s_add_u32 s0, s90, s0
	v_readlane_b32 s48, v246, 19
	v_readlane_b32 s49, v246, 20
	v_readlane_b32 s50, v246, 21
	v_readlane_b32 s51, v246, 22
	v_readlane_b32 s52, v246, 23
	v_readlane_b32 s53, v246, 24
	s_addc_u32 s1, s91, s1
	v_readlane_b32 s54, v246, 25
	v_readlane_b32 s55, v246, 26
	s_mov_b64 s[48:49], s[52:53]
	v_lshl_add_u64 v[76:77], s[0:1], 0, v[2:3]
	s_add_u32 s0, s48, s16
	s_addc_u32 s1, s49, 0
	v_lshl_add_u64 v[78:79], s[0:1], 0, v[2:3]
	v_readlane_b32 s0, v244, 17
	v_readlane_b32 s1, v244, 18
	v_ashrrev_i32_e32 v5, 31, v4
	v_lshlrev_b32_e32 v134, 5, v0
	v_lshl_add_u64 v[80:81], s[0:1], 0, v[2:3]
	v_lshlrev_b64 v[2:3], 12, v[4:5]
	v_or_b32_e32 v2, v2, v134
	v_lshlrev_b32_e32 v0, 4, v0
	v_subrev_u32_e32 v137, 32, v4
	v_lshl_add_u64 v[82:83], s[92:93], 0, v[2:3]
	v_lshl_add_u64 v[84:85], s[94:95], 0, v[0:1]
	v_lshlrev_b64 v[86:87], 11, v[4:5]
	s_and_b32 s100, s2, 7
	s_lshl_b32 s100, s100, 5
	s_lshr_b32 s101, s2, 3
	s_or_b32 s100, s100, s101
	s_cmp_eq_u32 s96, 0x100
	s_cselect_b32 s0, s100, s2
	v_readlane_b32 s41, v246, 12
	v_readlane_b32 s42, v246, 13
	v_readlane_b32 s43, v246, 14
	v_readlane_b32 s44, v246, 15
	v_readlane_b32 s45, v246, 16
	v_readlane_b32 s46, v246, 17
	v_readlane_b32 s47, v246, 18
	s_mov_b64 s[50:51], s[54:55]
	s_branch .LBB0_719
